# diff-attn key loops: wait for Q fragments once before the loop instead of vmcnt(3..0) inside QK each tile (no longer waits for the just-issued next-tile staging loads)
# speedup vs baseline: 1.0119x; 1.0119x over previous
.LBB0_34:
	s_lshl_b32 s1, s68, 1
	s_ashr_i32 s70, s69, 6
	s_and_b32 s36, s1, 0x700
	s_mul_i32 s28, s70, 0x1800000
	s_mul_hi_i32 s29, s70, 0x1800000
	s_add_u32 s1, s9, s28
	s_addc_u32 s4, s40, s29
	s_lshl_b32 s5, s69, 4
	s_and_b32 s71, s5, 0x380
	s_lshl_b32 s5, s71, 1
	s_add_u32 s48, s1, s5
	s_addc_u32 s49, s4, 0
	v_mov_b32_e32 v6, v227
	v_mov_b32_e32 v162, v226
	s_add_u32 s30, s48, 0x1000
	s_addc_u32 s31, s49, 0
	v_mov_b64_e32 v[2:3], s[48:49]
	v_ashrrev_i32_e32 v10, 3, v6
	s_movk_i32 s23, 0x1800
	v_lshlrev_b32_e32 v7, 4, v6
	s_lshl_b32 s1, s69, 8
	v_mad_i64_i32 v[4:5], s[4:5], v10, s23, v[2:3]
	v_and_b32_e32 v0, 0x70, v7
	v_and_b32_e32 v144, 0xf0, v7
	v_mov_b32_e32 v145, v1
	v_ashrrev_i32_e32 v11, 4, v6
	v_add_u32_e32 v6, 0x200, v6
	s_and_b32 s11, s1, 0x700
	v_lshl_add_u64 v[150:151], v[4:5], 0, v[0:1]
	v_lshl_add_u64 v[4:5], s[30:31], 0, v[144:145]
	v_ashrrev_i32_e32 v12, 4, v6
	s_xor_b32 s22, s11, 0xf00
	v_readlane_b32 s1, v251, 7
	v_mad_i64_i32 v[152:153], s[4:5], v11, s23, v[4:5]
	v_mad_i64_i32 v[154:155], s[4:5], v12, s23, v[4:5]
	v_and_b32_e32 v145, 31, v162
	v_ashrrev_i32_e32 v5, 5, v162
	s_add_i32 s1, s22, s1
	v_lshlrev_b32_e32 v4, 3, v5
	v_or_b32_e32 v176, s1, v145
	v_lshlrev_b32_e32 v172, 4, v5
	v_lshlrev_b32_e32 v173, 2, v5
	v_ashrrev_i32_e32 v5, 31, v4
	v_mad_u64_u32 v[2:3], s[4:5], v176, s23, v[2:3]
	v_lshl_add_u64 v[156:157], v[4:5], 1, v[2:3]
	global_load_dwordx4 v[114:117], v[150:151], off offset:2048
	global_load_dwordx4 v[118:121], v[152:153], off
	global_load_dwordx4 v[122:125], v[154:155], off
	global_load_dwordx4 v[126:129], v[156:157], off
	global_load_dwordx4 v[130:133], v[156:157], off offset:32
	global_load_dwordx4 v[134:137], v[156:157], off offset:64
	global_load_dwordx4 v[138:141], v[156:157], off offset:96
	v_lshrrev_b32_e32 v14, 2, v162
	v_mad_i64_i32 v[6:7], s[4:5], v10, s23, 0
	v_mad_i64_i32 v[8:9], s[4:5], v11, s23, 0
	v_mul_lo_u32 v163, v10, s96
	v_mul_lo_u32 v164, v11, s77
	v_mad_i64_i32 v[10:11], s[4:5], v12, s23, 0
	v_and_or_b32 v2, v14, 3, v173
	s_addk_i32 s22, 0x100
	v_mov_b32_e32 v4, 0x1800000
	v_mul_lo_u32 v178, v2, s77
	s_lshr_b32 s4, s22, 6
	v_mad_i64_i32 v[2:3], s[22:23], s70, v4, v[10:11]
	v_or3_b32 v2, v2, s36, v144
	v_lshlrev_b32_e32 v237, 2, v162
	v_and_b32_e32 v13, 16, v162
	v_add_u32_e32 v16, 0, v144
	v_mul_lo_u32 v175, v12, s77
	v_lshl_add_u64 v[146:147], s[16:17], 0, v[2:3]
	v_mad_i64_i32 v[2:3], s[22:23], s70, v4, v[8:9]
	v_and_or_b32 v13, v237, 12, v13
	v_add_u32_e32 v15, 0, v163
	v_add_u32_e32 v235, v16, v164
	v_add_u32_e32 v236, v16, v175
	v_or3_b32 v2, v2, s36, v144
	v_mad_i64_i32 v[158:159], s[22:23], s70, v4, v[6:7]
	v_mov_b32_e32 v16, v1
	v_mov_b32_e32 v17, v1
	v_lshlrev_b32_e32 v177, 1, v13
	v_add_u32_e32 v234, v15, v0
	v_lshl_add_u64 v[148:149], s[16:17], 0, v[2:3]
	v_or3_b32 v158, v158, s36, v0
	v_mov_b32_e32 v2, v1
	v_mov_b32_e32 v3, v1
	v_mov_b32_e32 v4, v1
	v_mov_b32_e32 v5, v1
	v_mov_b32_e32 v6, v1
	v_mov_b32_e32 v7, v1
	v_mov_b32_e32 v8, v1
	v_mov_b32_e32 v9, v1
	v_mov_b32_e32 v10, v1
	v_mov_b32_e32 v11, v1
	v_mov_b32_e32 v12, v1
	v_mov_b32_e32 v13, v1
	v_mov_b32_e32 v14, v1
	v_mov_b32_e32 v15, v1
	v_mov_b64_e32 v[64:65], v[16:17]
	v_mov_b64_e32 v[48:49], v[16:17]
	v_mov_b64_e32 v[32:33], v[16:17]
	v_mov_b64_e32 v[80:81], v[16:17]
	s_mov_b32 s10, 1
	v_cmp_gt_u32_e64 s[42:43], 32, v162
	v_mul_u32_u24_e32 v165, 0x90, v145
	v_lshl_add_u32 v174, v145, 2, s91
	s_or_b32 s5, s1, 31
	v_subrev_u32_e32 v179, 32, v176
	v_subrev_u32_e32 v180, 33, v176
	v_subrev_u32_e32 v181, 34, v176
	v_subrev_u32_e32 v182, 35, v176
	v_add_u32_e32 v183, -8, v176
	v_subrev_u32_e32 v184, 40, v176
	v_add_u32_e32 v185, -9, v176
	v_subrev_u32_e32 v186, 41, v176
	v_add_u32_e32 v187, -10, v176
	v_subrev_u32_e32 v188, 42, v176
	v_add_u32_e32 v189, -11, v176
	v_subrev_u32_e32 v195, 43, v176
	v_add_u32_e32 v196, -16, v176
	v_subrev_u32_e32 v197, 48, v176
	v_subrev_u32_e32 v198, 17, v176
	v_subrev_u32_e32 v199, 49, v176
	v_subrev_u32_e32 v200, 18, v176
	v_subrev_u32_e32 v201, 50, v176
	v_subrev_u32_e32 v202, 19, v176
	v_subrev_u32_e32 v203, 51, v176
	v_subrev_u32_e32 v204, 24, v176
	v_subrev_u32_e32 v205, 56, v176
	v_subrev_u32_e32 v228, 25, v176
	v_subrev_u32_e32 v229, 57, v176
	v_subrev_u32_e32 v230, 26, v176
	v_subrev_u32_e32 v231, 58, v176
	v_subrev_u32_e32 v232, 27, v176
	v_subrev_u32_e32 v233, 59, v176
	v_lshl_add_u64 v[160:161], s[44:45], 0, v[158:159]
	v_mov_b32_e32 v239, 0xff800000
	s_mov_b32 s22, 63
	s_mov_b64 s[50:51], 0
	v_mov_b64_e32 v[62:63], v[14:15]
	v_mov_b64_e32 v[60:61], v[12:13]
	v_mov_b64_e32 v[58:59], v[10:11]
	v_mov_b64_e32 v[56:57], v[8:9]
	v_mov_b64_e32 v[54:55], v[6:7]
	v_mov_b64_e32 v[52:53], v[4:5]
	v_mov_b64_e32 v[50:51], v[2:3]
	v_mov_b64_e32 v[46:47], v[14:15]
	v_mov_b64_e32 v[44:45], v[12:13]
	v_mov_b64_e32 v[42:43], v[10:11]
	v_mov_b64_e32 v[40:41], v[8:9]
	v_mov_b64_e32 v[38:39], v[6:7]
	v_mov_b64_e32 v[36:37], v[4:5]
	v_mov_b64_e32 v[34:35], v[2:3]
	v_mov_b64_e32 v[30:31], v[14:15]
	v_mov_b64_e32 v[28:29], v[12:13]
	v_mov_b64_e32 v[26:27], v[10:11]
	v_mov_b64_e32 v[24:25], v[8:9]
	v_mov_b64_e32 v[22:23], v[6:7]
	v_mov_b64_e32 v[20:21], v[4:5]
	v_mov_b64_e32 v[18:19], v[2:3]
	v_mov_b64_e32 v[78:79], v[14:15]
	v_mov_b64_e32 v[76:77], v[12:13]
	v_mov_b64_e32 v[74:75], v[10:11]
	v_mov_b64_e32 v[72:73], v[8:9]
	v_mov_b64_e32 v[70:71], v[6:7]
	v_mov_b64_e32 v[68:69], v[4:5]
	v_mov_b64_e32 v[66:67], v[2:3]
	s_waitcnt vmcnt(6)
	ds_write_b128 v234, v[114:117]
	s_waitcnt vmcnt(5)
	ds_write_b128 v235, v[118:121] offset:9216
	s_waitcnt vmcnt(4)
	ds_write_b128 v236, v[122:125] offset:9216
	s_waitcnt vmcnt(0) lgkmcnt(0)
	s_barrier
	s_cmp_lt_u32 s10, s4
	s_cselect_b64 s[60:61], -1, 0
	s_cmp_ge_u32 s10, s4
	s_cbranch_scc1 .LBB0_36

.LBB0_36:
	s_add_i32 s23, s10, -1
	s_and_b32 s23, s23, 1
	s_sub_i32 s26, s22, 63
	s_cmp_gt_u32 s26, s5
	s_cbranch_scc1 .LBB0_43
	s_mul_i32 s26, s23, 0x6900
	s_add_i32 s26, s26, 0
	v_add3_u32 v190, s26, v165, v172
	ds_read_b128 v[82:85], v190
	ds_read_b128 v[240:243], v190 offset:32
	ds_read_b128 v[98:101], v190 offset:4608
	s_cmp_le_u32 s22, s1
	s_waitcnt lgkmcnt(2)
	v_mfma_f32_32x32x16_bf16 v[82:97], v[82:85], v[126:129], 0
	s_waitcnt lgkmcnt(1)
	v_mfma_f32_32x32x16_bf16 v[82:97], v[240:243], v[130:133], v[82:97]
	ds_read_b128 v[240:243], v190 offset:4640
	s_waitcnt lgkmcnt(1)
	v_mfma_f32_32x32x16_bf16 v[98:113], v[98:101], v[126:129], 0
	s_waitcnt lgkmcnt(0)
	v_mfma_f32_32x32x16_bf16 v[98:113], v[240:243], v[130:133], v[98:113]
	ds_read_b128 v[240:243], v190 offset:64
	s_waitcnt lgkmcnt(0)
	v_mfma_f32_32x32x16_bf16 v[82:97], v[240:243], v[134:137], v[82:97]
	ds_read_b128 v[240:243], v190 offset:4672
	s_waitcnt lgkmcnt(0)
	v_mfma_f32_32x32x16_bf16 v[98:113], v[240:243], v[134:137], v[98:113]
	ds_read_b128 v[240:243], v190 offset:96
	s_waitcnt lgkmcnt(0)
	v_mfma_f32_32x32x16_bf16 v[82:97], v[240:243], v[138:141], v[82:97]
	ds_read_b128 v[240:243], v190 offset:4704
	s_waitcnt lgkmcnt(0)
	v_mfma_f32_32x32x16_bf16 v[98:113], v[240:243], v[138:141], v[98:113]
	s_cbranch_scc1 .LBB0_39
	v_add_u32_e32 v190, s22, v173
	v_subrev_u32_e32 v191, 63, v190
	v_cmp_le_i32_e32 vcc, v191, v179
	v_subrev_u32_e32 v192, 61, v190
	v_subrev_u32_e32 v190, 60, v190
	s_nop 5
	v_cndmask_b32_e32 v98, v220, v98, vcc
	v_cmp_lt_i32_e32 vcc, v191, v176
	s_nop 1
	v_cndmask_b32_e32 v83, v220, v83, vcc
	v_cmp_le_i32_e32 vcc, v191, v176
	s_nop 1
	v_cndmask_b32_e32 v82, v220, v82, vcc
	v_cmp_le_i32_e32 vcc, v191, v180
	s_nop 1
	v_cndmask_b32_e32 v99, v220, v99, vcc
	v_cmp_le_i32_e32 vcc, v192, v176
	s_nop 1
	v_cndmask_b32_e32 v84, v220, v84, vcc
	v_cmp_le_i32_e32 vcc, v191, v181
	s_nop 1
	v_cndmask_b32_e32 v100, v220, v100, vcc
	v_cmp_le_i32_e32 vcc, v190, v176
	s_nop 1
	v_cndmask_b32_e32 v85, v220, v85, vcc
	v_cmp_le_i32_e32 vcc, v191, v182
	s_nop 1
	v_cndmask_b32_e32 v101, v220, v101, vcc
	v_cmp_le_i32_e32 vcc, v191, v183
	s_nop 1
	v_cndmask_b32_e32 v86, v220, v86, vcc
	v_cmp_le_i32_e32 vcc, v191, v184
	s_nop 1
	v_cndmask_b32_e32 v102, v220, v102, vcc
	v_cmp_le_i32_e32 vcc, v191, v185
	s_nop 1
	v_cndmask_b32_e32 v87, v220, v87, vcc
	v_cmp_le_i32_e32 vcc, v191, v186
	s_nop 1
	v_cndmask_b32_e32 v103, v220, v103, vcc
	v_cmp_le_i32_e32 vcc, v191, v187
	s_nop 1
	v_cndmask_b32_e32 v88, v220, v88, vcc
	v_cmp_le_i32_e32 vcc, v191, v188
	s_nop 1
	v_cndmask_b32_e32 v104, v220, v104, vcc
	v_cmp_le_i32_e32 vcc, v191, v189
	s_nop 1
	v_cndmask_b32_e32 v89, v220, v89, vcc
	v_cmp_le_i32_e32 vcc, v191, v195
	s_nop 1
	v_cndmask_b32_e32 v105, v220, v105, vcc
	v_cmp_le_i32_e32 vcc, v191, v196
	s_nop 1
	v_cndmask_b32_e32 v90, v220, v90, vcc
	v_cmp_le_i32_e32 vcc, v191, v197
	s_nop 1
	v_cndmask_b32_e32 v106, v220, v106, vcc
	v_cmp_le_i32_e32 vcc, v191, v198
	s_nop 1
	v_cndmask_b32_e32 v91, v220, v91, vcc
	v_cmp_le_i32_e32 vcc, v191, v199
	s_nop 1
	v_cndmask_b32_e32 v107, v220, v107, vcc
	v_cmp_le_i32_e32 vcc, v191, v200
	s_nop 1
	v_cndmask_b32_e32 v92, v220, v92, vcc
	v_cmp_le_i32_e32 vcc, v191, v201
	s_nop 1
	v_cndmask_b32_e32 v108, v220, v108, vcc
	v_cmp_le_i32_e32 vcc, v191, v202
	s_nop 1
	v_cndmask_b32_e32 v93, v220, v93, vcc
	v_cmp_le_i32_e32 vcc, v191, v203
	s_nop 1
	v_cndmask_b32_e32 v109, v220, v109, vcc
	v_cmp_le_i32_e32 vcc, v191, v204
	s_nop 1
	v_cndmask_b32_e32 v94, v220, v94, vcc
	v_cmp_le_i32_e32 vcc, v191, v205
	s_nop 1
	v_cndmask_b32_e32 v110, v220, v110, vcc
	v_cmp_le_i32_e32 vcc, v191, v228
	s_nop 1
	v_cndmask_b32_e32 v95, v220, v95, vcc
	v_cmp_le_i32_e32 vcc, v191, v229
	s_nop 1
	v_cndmask_b32_e32 v111, v220, v111, vcc
	v_cmp_le_i32_e32 vcc, v191, v230
	s_nop 1
	v_cndmask_b32_e32 v96, v220, v96, vcc
	v_cmp_le_i32_e32 vcc, v191, v231
	s_nop 1
	v_cndmask_b32_e32 v112, v220, v112, vcc
	v_cmp_le_i32_e32 vcc, v191, v232
	s_nop 1
	v_cndmask_b32_e32 v97, v220, v97, vcc
	v_cmp_le_i32_e32 vcc, v191, v233
	s_nop 1
	v_cndmask_b32_e32 v113, v220, v113, vcc

.LBB0_49:
	v_mov_b32_e32 v82, v2
	v_rcp_f32_e32 v2, v67
	v_mov_b32_e32 v83, v50
	v_mov_b32_e32 v85, v18
	v_mov_b32_e32 v50, v3
	v_mov_b32_e32 v18, v35
	v_pk_mul_f32 v[50:51], v[50:51], v[2:3] op_sel_hi:[1,0]
	v_pk_mul_f32 v[2:3], v[18:19], v[2:3] op_sel_hi:[1,0]
	v_mov_b32_e32 v18, v4
	v_rcp_f32_e32 v4, v69
	v_mov_b32_e32 v84, v34
	v_rcp_f32_e32 v34, v68
	v_mov_b32_e32 v19, v52
	v_mov_b32_e32 v69, v20
	v_mov_b32_e32 v52, v5
	v_mov_b32_e32 v20, v37
	v_pk_mul_f32 v[52:53], v[52:53], v[4:5] op_sel_hi:[1,0]
	v_pk_mul_f32 v[4:5], v[20:21], v[4:5] op_sel_hi:[1,0]
	v_mov_b32_e32 v20, v6
	v_rcp_f32_e32 v6, v71
	v_mov_b32_e32 v68, v36
	v_pk_mul_f32 v[18:19], v[18:19], v[34:35] op_sel_hi:[1,0]
	v_pk_mul_f32 v[34:35], v[68:69], v[34:35] op_sel_hi:[1,0]
	v_rcp_f32_e32 v36, v70
	v_mov_b32_e32 v21, v54
	v_mov_b32_e32 v69, v22
	v_mov_b32_e32 v54, v7
	v_mov_b32_e32 v22, v39
	v_pk_mul_f32 v[54:55], v[54:55], v[6:7] op_sel_hi:[1,0]
	v_pk_mul_f32 v[6:7], v[22:23], v[6:7] op_sel_hi:[1,0]
	v_mov_b32_e32 v22, v8
	v_rcp_f32_e32 v8, v73
	v_mov_b32_e32 v68, v38
	v_pk_mul_f32 v[20:21], v[20:21], v[36:37] op_sel_hi:[1,0]
	v_pk_mul_f32 v[36:37], v[68:69], v[36:37] op_sel_hi:[1,0]
	v_rcp_f32_e32 v38, v72
	v_mov_b32_e32 v23, v56
	v_mov_b32_e32 v69, v24
	v_mov_b32_e32 v56, v9
	v_mov_b32_e32 v24, v41
	v_pk_mul_f32 v[56:57], v[56:57], v[8:9] op_sel_hi:[1,0]
	v_pk_mul_f32 v[8:9], v[24:25], v[8:9] op_sel_hi:[1,0]
	v_mov_b32_e32 v24, v10
	v_rcp_f32_e32 v10, v75
	v_mov_b32_e32 v68, v40
	v_pk_mul_f32 v[22:23], v[22:23], v[38:39] op_sel_hi:[1,0]
	v_pk_mul_f32 v[38:39], v[68:69], v[38:39] op_sel_hi:[1,0]
	v_rcp_f32_e32 v40, v74
	v_mov_b32_e32 v25, v58
	v_mov_b32_e32 v69, v26
	v_mov_b32_e32 v58, v11
	v_mov_b32_e32 v26, v43
	v_pk_mul_f32 v[58:59], v[58:59], v[10:11] op_sel_hi:[1,0]
	v_pk_mul_f32 v[10:11], v[26:27], v[10:11] op_sel_hi:[1,0]
	v_mov_b32_e32 v26, v12
	v_rcp_f32_e32 v12, v77
	v_mov_b32_e32 v68, v42
	v_pk_mul_f32 v[24:25], v[24:25], v[40:41] op_sel_hi:[1,0]
	v_pk_mul_f32 v[40:41], v[68:69], v[40:41] op_sel_hi:[1,0]
	v_rcp_f32_e32 v42, v76
	v_mov_b32_e32 v27, v60
	v_mov_b32_e32 v69, v28
	v_mov_b32_e32 v60, v13
	v_mov_b32_e32 v28, v45
	v_pk_mul_f32 v[60:61], v[60:61], v[12:13] op_sel_hi:[1,0]
	v_pk_mul_f32 v[12:13], v[28:29], v[12:13] op_sel_hi:[1,0]
	v_mov_b32_e32 v28, v14
	v_rcp_f32_e32 v14, v79
	v_mov_b32_e32 v68, v44
	v_rcp_f32_e32 v66, v66
	v_pk_mul_f32 v[26:27], v[26:27], v[42:43] op_sel_hi:[1,0]
	v_pk_mul_f32 v[42:43], v[68:69], v[42:43] op_sel_hi:[1,0]
	v_rcp_f32_e32 v44, v78
	v_mov_b32_e32 v29, v62
	v_mov_b32_e32 v69, v30
	v_mov_b32_e32 v62, v15
	v_mov_b32_e32 v30, v47
	v_pk_mul_f32 v[62:63], v[62:63], v[14:15] op_sel_hi:[1,0]
	v_pk_mul_f32 v[14:15], v[30:31], v[14:15] op_sel_hi:[1,0]
	v_mov_b32_e32 v30, v16
	v_rcp_f32_e32 v16, v81
	v_readlane_b32 s10, v251, 9
	v_mov_b32_e32 v68, v46
	v_pk_mul_f32 v[82:83], v[82:83], v[66:67] op_sel_hi:[1,0]
	v_add_u32_e32 v160, s10, v237
	v_pk_mul_f32 v[66:67], v[84:85], v[66:67] op_sel_hi:[1,0]
	v_pk_mul_f32 v[28:29], v[28:29], v[44:45] op_sel_hi:[1,0]
	v_pk_mul_f32 v[44:45], v[68:69], v[44:45] op_sel_hi:[1,0]
	v_mov_b32_e32 v31, v64
	v_mov_b32_e32 v69, v32
	v_mov_b32_e32 v64, v17
	v_mov_b32_e32 v32, v49
	v_mov_b32_e32 v68, v48
	v_pk_mul_f32 v[64:65], v[64:65], v[16:17] op_sel_hi:[1,0]
	v_pk_mul_f32 v[16:17], v[32:33], v[16:17] op_sel_hi:[1,0]
	v_cvt_pk_bf16_f32 v33, v82, v83
	v_add_u32_e32 v32, 0, v160
	v_cvt_pk_bf16_f32 v48, v66, v67
	ds_write2st64_b32 v32, v33, v48 offset1:1
	v_cvt_pk_bf16_f32 v33, v50, v51
	v_cvt_pk_bf16_f32 v2, v2, v3
	ds_write2st64_b32 v32, v33, v2 offset0:2 offset1:3
	v_cvt_pk_bf16_f32 v2, v18, v19
	v_cvt_pk_bf16_f32 v3, v34, v35
	ds_write2st64_b32 v32, v2, v3 offset0:4 offset1:5
	v_cvt_pk_bf16_f32 v2, v52, v53
	v_cvt_pk_bf16_f32 v3, v4, v5
	ds_write2st64_b32 v32, v2, v3 offset0:6 offset1:7
	v_cvt_pk_bf16_f32 v2, v20, v21
	v_cvt_pk_bf16_f32 v3, v36, v37
	ds_write2st64_b32 v32, v2, v3 offset0:8 offset1:9
	v_cvt_pk_bf16_f32 v2, v54, v55
	v_cvt_pk_bf16_f32 v3, v6, v7
	ds_write2st64_b32 v32, v2, v3 offset0:10 offset1:11
	v_cvt_pk_bf16_f32 v2, v22, v23
	v_cvt_pk_bf16_f32 v3, v38, v39
	ds_write2st64_b32 v32, v2, v3 offset0:12 offset1:13
	v_cvt_pk_bf16_f32 v2, v56, v57
	v_cvt_pk_bf16_f32 v3, v8, v9
	ds_write2st64_b32 v32, v2, v3 offset0:14 offset1:15
	v_cvt_pk_bf16_f32 v2, v24, v25
	v_cvt_pk_bf16_f32 v3, v40, v41
	v_rcp_f32_e32 v46, v80
	ds_write2st64_b32 v32, v2, v3 offset0:16 offset1:17
	v_cvt_pk_bf16_f32 v2, v58, v59
	v_cvt_pk_bf16_f32 v3, v10, v11
	ds_write2st64_b32 v32, v2, v3 offset0:18 offset1:19
	v_cvt_pk_bf16_f32 v2, v26, v27
	v_cvt_pk_bf16_f32 v3, v42, v43
	ds_write2st64_b32 v32, v2, v3 offset0:20 offset1:21
	v_cvt_pk_bf16_f32 v2, v60, v61
	v_cvt_pk_bf16_f32 v3, v12, v13
	ds_write2st64_b32 v32, v2, v3 offset0:22 offset1:23
	v_cvt_pk_bf16_f32 v2, v28, v29
	v_cvt_pk_bf16_f32 v3, v44, v45
	v_pk_mul_f32 v[30:31], v[30:31], v[46:47] op_sel_hi:[1,0]
	v_pk_mul_f32 v[46:47], v[68:69], v[46:47] op_sel_hi:[1,0]
	ds_write2st64_b32 v32, v2, v3 offset0:24 offset1:25
	v_cvt_pk_bf16_f32 v2, v62, v63
	v_cvt_pk_bf16_f32 v3, v14, v15
	ds_write2st64_b32 v32, v2, v3 offset0:26 offset1:27
	v_cvt_pk_bf16_f32 v2, v30, v31
	v_cvt_pk_bf16_f32 v3, v46, v47
	ds_write2st64_b32 v32, v2, v3 offset0:28 offset1:29
	v_cvt_pk_bf16_f32 v2, v64, v65
	v_cvt_pk_bf16_f32 v3, v16, v17
	ds_write2st64_b32 v32, v2, v3 offset0:30 offset1:31
	global_load_dwordx4 v[122:125], v[150:151], off offset:2176
	global_load_dwordx4 v[134:137], v[152:153], off
	global_load_dwordx4 v[138:141], v[154:155], off
	global_load_dwordx4 v[114:117], v[156:157], off offset:128
	global_load_dwordx4 v[118:121], v[156:157], off offset:160
	global_load_dwordx4 v[126:129], v[156:157], off offset:192
	global_load_dwordx4 v[130:133], v[156:157], off offset:224
	v_mov_b32_e32 v16, v1
	v_mov_b32_e32 v17, v1
	v_mov_b32_e32 v2, v1
	v_mov_b32_e32 v3, v1
	v_mov_b32_e32 v4, v1
	v_mov_b32_e32 v5, v1
	v_mov_b32_e32 v6, v1
	v_mov_b32_e32 v7, v1
	v_mov_b32_e32 v8, v1
	v_mov_b32_e32 v9, v1
	v_mov_b32_e32 v10, v1
	v_mov_b32_e32 v11, v1
	v_mov_b32_e32 v12, v1
	v_mov_b32_e32 v13, v1
	v_mov_b32_e32 v14, v1
	v_mov_b32_e32 v15, v1
	v_mov_b64_e32 v[64:65], v[16:17]
	v_mov_b64_e32 v[32:33], v[16:17]
	v_mov_b64_e32 v[48:49], v[16:17]
	v_mov_b64_e32 v[80:81], v[16:17]
	v_lshl_add_u64 v[150:151], s[46:47], 0, v[158:159]
	v_mov_b32_e32 v153, 0xff800000
	s_mov_b32 s10, 63
	s_mov_b64 s[60:61], 0
	s_mov_b32 s22, 1
	v_mov_b64_e32 v[62:63], v[14:15]
	v_mov_b64_e32 v[60:61], v[12:13]
	v_mov_b64_e32 v[58:59], v[10:11]
	v_mov_b64_e32 v[56:57], v[8:9]
	v_mov_b64_e32 v[54:55], v[6:7]
	v_mov_b64_e32 v[52:53], v[4:5]
	v_mov_b64_e32 v[50:51], v[2:3]
	v_mov_b64_e32 v[30:31], v[14:15]
	v_mov_b64_e32 v[28:29], v[12:13]
	v_mov_b64_e32 v[26:27], v[10:11]
	v_mov_b64_e32 v[24:25], v[8:9]
	v_mov_b64_e32 v[22:23], v[6:7]
	v_mov_b64_e32 v[20:21], v[4:5]
	v_mov_b64_e32 v[18:19], v[2:3]
	v_mov_b64_e32 v[46:47], v[14:15]
	v_mov_b64_e32 v[44:45], v[12:13]
	v_mov_b64_e32 v[42:43], v[10:11]
	v_mov_b64_e32 v[40:41], v[8:9]
	v_mov_b64_e32 v[38:39], v[6:7]
	v_mov_b64_e32 v[36:37], v[4:5]
	v_mov_b64_e32 v[34:35], v[2:3]
	v_mov_b64_e32 v[78:79], v[14:15]
	v_mov_b64_e32 v[76:77], v[12:13]
	v_mov_b64_e32 v[74:75], v[10:11]
	v_mov_b64_e32 v[72:73], v[8:9]
	v_mov_b64_e32 v[70:71], v[6:7]
	v_mov_b64_e32 v[68:69], v[4:5]
	v_mov_b64_e32 v[66:67], v[2:3]
	s_waitcnt vmcnt(6)
	ds_write_b128 v234, v[122:125]
	s_waitcnt vmcnt(5)
	ds_write_b128 v235, v[134:137] offset:9216
	s_waitcnt vmcnt(4)
	ds_write_b128 v236, v[138:141] offset:9216
	s_waitcnt vmcnt(0) lgkmcnt(0)
	s_barrier
	s_cmp_lt_u32 s22, s4
	s_cselect_b64 s[62:63], -1, 0
	s_cmp_ge_u32 s22, s4
	s_cbranch_scc1 .LBB0_51

.LBB0_51:
	s_add_i32 s23, s22, -1
	s_and_b32 s23, s23, 1
	s_sub_i32 s26, s10, 63
	s_cmp_gt_u32 s26, s5
	s_cbranch_scc1 .LBB0_58
	s_mul_i32 s26, s23, 0x6900
	s_add_i32 s26, s26, 0
	v_add3_u32 v152, s26, v165, v172
	ds_read_b128 v[82:85], v152
	ds_read_b128 v[154:157], v152 offset:32
	ds_read_b128 v[98:101], v152 offset:4608
	s_cmp_le_u32 s10, s1
	s_waitcnt lgkmcnt(2)
	v_mfma_f32_32x32x16_bf16 v[82:97], v[82:85], v[114:117], 0
	s_waitcnt lgkmcnt(1)
	v_mfma_f32_32x32x16_bf16 v[82:97], v[154:157], v[118:121], v[82:97]
	ds_read_b128 v[154:157], v152 offset:4640
	s_waitcnt lgkmcnt(1)
	v_mfma_f32_32x32x16_bf16 v[98:113], v[98:101], v[114:117], 0
	s_waitcnt lgkmcnt(0)
	v_mfma_f32_32x32x16_bf16 v[98:113], v[154:157], v[118:121], v[98:113]
	ds_read_b128 v[154:157], v152 offset:64
	s_waitcnt lgkmcnt(0)
	v_mfma_f32_32x32x16_bf16 v[82:97], v[154:157], v[126:129], v[82:97]
	ds_read_b128 v[154:157], v152 offset:4672
	s_waitcnt lgkmcnt(0)
	v_mfma_f32_32x32x16_bf16 v[98:113], v[154:157], v[126:129], v[98:113]
	ds_read_b128 v[154:157], v152 offset:96
	s_waitcnt lgkmcnt(0)
	v_mfma_f32_32x32x16_bf16 v[82:97], v[154:157], v[130:133], v[82:97]
	ds_read_b128 v[154:157], v152 offset:4704
	s_waitcnt lgkmcnt(0)
	v_mfma_f32_32x32x16_bf16 v[98:113], v[154:157], v[130:133], v[98:113]
	s_cbranch_scc1 .LBB0_54
	v_add_u32_e32 v152, s10, v173
	v_subrev_u32_e32 v154, 63, v152
	v_cmp_le_i32_e32 vcc, v154, v179
	v_subrev_u32_e32 v155, 61, v152
	v_subrev_u32_e32 v152, 60, v152
	s_nop 5
	v_cndmask_b32_e32 v98, v220, v98, vcc
	v_cmp_lt_i32_e32 vcc, v154, v176
	s_nop 1
	v_cndmask_b32_e32 v83, v220, v83, vcc
	v_cmp_le_i32_e32 vcc, v154, v176
	s_nop 1
	v_cndmask_b32_e32 v82, v220, v82, vcc
	v_cmp_le_i32_e32 vcc, v154, v180
	s_nop 1
	v_cndmask_b32_e32 v99, v220, v99, vcc
	v_cmp_le_i32_e32 vcc, v155, v176
	s_nop 1
	v_cndmask_b32_e32 v84, v220, v84, vcc
	v_cmp_le_i32_e32 vcc, v154, v181
	s_nop 1
	v_cndmask_b32_e32 v100, v220, v100, vcc
	v_cmp_le_i32_e32 vcc, v152, v176
	s_nop 1
	v_cndmask_b32_e32 v85, v220, v85, vcc
	v_cmp_le_i32_e32 vcc, v154, v182
	s_nop 1
	v_cndmask_b32_e32 v101, v220, v101, vcc
	v_cmp_le_i32_e32 vcc, v154, v183
	s_nop 1
	v_cndmask_b32_e32 v86, v220, v86, vcc
	v_cmp_le_i32_e32 vcc, v154, v184
	s_nop 1
	v_cndmask_b32_e32 v102, v220, v102, vcc
	v_cmp_le_i32_e32 vcc, v154, v185
	s_nop 1
	v_cndmask_b32_e32 v87, v220, v87, vcc
	v_cmp_le_i32_e32 vcc, v154, v186
	s_nop 1
	v_cndmask_b32_e32 v103, v220, v103, vcc
	v_cmp_le_i32_e32 vcc, v154, v187
	s_nop 1
	v_cndmask_b32_e32 v88, v220, v88, vcc
	v_cmp_le_i32_e32 vcc, v154, v188
	s_nop 1
	v_cndmask_b32_e32 v104, v220, v104, vcc
	v_cmp_le_i32_e32 vcc, v154, v189
	s_nop 1
	v_cndmask_b32_e32 v89, v220, v89, vcc
	v_cmp_le_i32_e32 vcc, v154, v195
	s_nop 1
	v_cndmask_b32_e32 v105, v220, v105, vcc
	v_cmp_le_i32_e32 vcc, v154, v196
	s_nop 1
	v_cndmask_b32_e32 v90, v220, v90, vcc
	v_cmp_le_i32_e32 vcc, v154, v197
	s_nop 1
	v_cndmask_b32_e32 v106, v220, v106, vcc
	v_cmp_le_i32_e32 vcc, v154, v198
	s_nop 1
	v_cndmask_b32_e32 v91, v220, v91, vcc
	v_cmp_le_i32_e32 vcc, v154, v199
	s_nop 1
	v_cndmask_b32_e32 v107, v220, v107, vcc
	v_cmp_le_i32_e32 vcc, v154, v200
	s_nop 1
	v_cndmask_b32_e32 v92, v220, v92, vcc
	v_cmp_le_i32_e32 vcc, v154, v201
	s_nop 1
	v_cndmask_b32_e32 v108, v220, v108, vcc
	v_cmp_le_i32_e32 vcc, v154, v202
	s_nop 1
	v_cndmask_b32_e32 v93, v220, v93, vcc
	v_cmp_le_i32_e32 vcc, v154, v203
	s_nop 1
	v_cndmask_b32_e32 v109, v220, v109, vcc
	v_cmp_le_i32_e32 vcc, v154, v204
	s_nop 1
	v_cndmask_b32_e32 v94, v220, v94, vcc
	v_cmp_le_i32_e32 vcc, v154, v205
	s_nop 1
	v_cndmask_b32_e32 v110, v220, v110, vcc
	v_cmp_le_i32_e32 vcc, v154, v228
	s_nop 1
	v_cndmask_b32_e32 v95, v220, v95, vcc
	v_cmp_le_i32_e32 vcc, v154, v229
	s_nop 1
	v_cndmask_b32_e32 v111, v220, v111, vcc
	v_cmp_le_i32_e32 vcc, v154, v230
	s_nop 1
	v_cndmask_b32_e32 v96, v220, v96, vcc
	v_cmp_le_i32_e32 vcc, v154, v231
	s_nop 1
	v_cndmask_b32_e32 v112, v220, v112, vcc
	v_cmp_le_i32_e32 vcc, v154, v232
	s_nop 1
	v_cndmask_b32_e32 v97, v220, v97, vcc
	v_cmp_le_i32_e32 vcc, v154, v233
	s_nop 1
	v_cndmask_b32_e32 v113, v220, v113, vcc

.LBB0_64:
	v_readlane_b32 s4, v255, 34
	v_readlane_b32 s5, v255, 35
	s_load_dwordx2 s[50:51], s[4:5], 0xb0
	v_rcp_f32_e32 v94, v69
	v_lshlrev_b32_e32 v69, 2, v145
	v_rcp_f32_e32 v98, v67
	v_rcp_f32_e32 v90, v71
	v_rcp_f32_e32 v86, v73
	s_waitcnt lgkmcnt(0)
	global_load_dword v67, v69, s[50:51]
	global_load_dword v71, v69, s[50:51] offset:128
	global_load_dword v73, v69, s[50:51] offset:256
	v_readlane_b32 s4, v251, 48
	global_load_dword v69, v69, s[50:51] offset:384
	v_rcp_f32_e32 v82, v75
	v_rcp_f32_e32 v96, v68
	v_rcp_f32_e32 v68, v79
	v_rcp_f32_e32 v88, v72
	v_rcp_f32_e32 v84, v74
	v_rcp_f32_e32 v74, v76
	v_rcp_f32_e32 v72, v77
	v_rcp_f32_e32 v100, v66
	v_mov_b32_e32 v106, v34
	v_mov_b32_e32 v107, v18
	s_mov_b32 s5, 0x800000
	v_rcp_f32_e32 v66, v80
	v_ashrrev_i32_e32 v80, 3, v162
	v_rcp_f32_e32 v92, v70
	v_rcp_f32_e32 v70, v78
	v_rcp_f32_e32 v0, v81
	v_and_b32_e32 v81, 0xffffffc, v80
	s_and_b32 s10, s67, 0x700
	s_addk_i32 s10, 0x100
	s_waitcnt vmcnt(3)
	v_mul_f32_e32 v67, 0x3f24fd5c, v67
	s_waitcnt vmcnt(2)
	v_mul_f32_e32 v71, 0x3f24fd5c, v71
	s_waitcnt vmcnt(1)
	v_mul_f32_e32 v73, 0x3f24fd5c, v73
	s_waitcnt vmcnt(0)
	v_mul_f32_e32 v75, 0x3f24fd5c, v69
	v_mov_b32_e32 v69, s4
	s_mov_b32 s4, 1
	v_add_u32_e32 v79, 0, v160
	ds_read2st64_b32 v[76:77], v79 offset1:1
	v_add_u32_e32 v69, 0, v69
	v_lshl_add_u32 v78, v145, 1, v69
	s_waitcnt lgkmcnt(0)
	v_lshlrev_b32_e32 v102, 16, v76
	v_and_b32_e32 v103, 0xffff0000, v76
	v_lshlrev_b32_e32 v105, 16, v77
	v_and_b32_e32 v104, 0xffff0000, v77
	v_mov_b32_e32 v76, v2
	v_mov_b32_e32 v77, v50
	v_pk_mul_f32 v[76:77], v[76:77], v[100:101] op_sel_hi:[1,0]
	v_pk_mul_f32 v[100:101], v[106:107], v[100:101] op_sel_hi:[1,0]
	v_pk_fma_f32 v[102:103], v[142:143], v[76:77], v[102:103] neg_lo:[1,0,0] neg_hi:[1,0,0]
	v_pk_fma_f32 v[100:101], v[142:143], v[100:101], v[104:105] neg_lo:[1,0,0] neg_hi:[1,0,0]
	v_pk_mul_f32 v[76:77], v[102:103], v[102:103]
	v_pk_mul_f32 v[104:105], v[100:101], v[100:101]
	v_add_f32_e32 v2, v76, v77
	v_add_f32_e32 v2, v2, v105
	v_add_f32_e32 v2, v104, v2
	ds_bpermute_b32 v18, v166, v2
	v_mad_u64_u32 v[76:77], s[22:23], v81, s77, v[78:79]
	s_waitcnt lgkmcnt(0)
	v_add_f32_e32 v2, v2, v18
	ds_bpermute_b32 v18, v167, v2
	s_waitcnt lgkmcnt(0)
	v_add_f32_e32 v2, v2, v18
	ds_bpermute_b32 v18, v168, v2
	s_waitcnt lgkmcnt(0)
	v_add_f32_e32 v2, v2, v18
	ds_bpermute_b32 v18, v169, v2
	s_waitcnt lgkmcnt(0)
	v_add_f32_e32 v2, v2, v18
	ds_bpermute_b32 v18, v170, v2
	s_waitcnt lgkmcnt(0)
	v_add_f32_e32 v2, v2, v18
	v_fmamk_f32 v2, v2, 0x3c000000, v249
	v_cmp_gt_f32_e32 vcc, s5, v2
	v_mul_f32_e32 v18, 0x4b800000, v2
	s_nop 0
	v_cndmask_b32_e32 v2, v2, v18, vcc
	v_rsq_f32_e32 v2, v2
	s_nop 0
	v_mul_f32_e32 v18, 0x45800000, v2
	v_cndmask_b32_e32 v2, v2, v18, vcc
	v_mul_f32_e32 v18, v102, v2
	v_mul_f32_e32 v18, v67, v18
	v_cvt_pk_bf16_f32 v18, v18, s0
	ds_write_b16 v76, v18
	v_mul_f32_e32 v18, v103, v2
	v_mul_f32_e32 v18, v71, v18
	v_cvt_pk_bf16_f32 v18, v18, s0
	ds_write_b16 v76, v18 offset:64
	v_mul_f32_e32 v18, v101, v2
	v_mul_f32_e32 v2, v100, v2
	v_mul_f32_e32 v18, v73, v18
	v_mul_f32_e32 v2, v75, v2
	v_cvt_pk_bf16_f32 v18, v18, s0
	v_cvt_pk_bf16_f32 v2, v2, s0
	ds_write_b16 v76, v18 offset:128
	ds_write_b16 v76, v2 offset:192
	ds_read2st64_b32 v[100:101], v79 offset0:2 offset1:3
	v_mov_b32_e32 v50, v3
	v_pk_mul_f32 v[50:51], v[50:51], v[98:99] op_sel_hi:[1,0]
	v_mov_b32_e32 v18, v35
	v_pk_mul_f32 v[18:19], v[18:19], v[98:99] op_sel_hi:[1,0]
	s_waitcnt lgkmcnt(0)
	v_lshlrev_b32_e32 v2, 16, v100
	v_and_b32_e32 v3, 0xffff0000, v100
	v_lshlrev_b32_e32 v103, 16, v101
	v_and_b32_e32 v102, 0xffff0000, v101
	v_pk_fma_f32 v[2:3], v[142:143], v[50:51], v[2:3] neg_lo:[1,0,0] neg_hi:[1,0,0]
	v_pk_fma_f32 v[18:19], v[142:143], v[18:19], v[102:103] neg_lo:[1,0,0] neg_hi:[1,0,0]
	v_pk_mul_f32 v[50:51], v[2:3], v[2:3]
	v_pk_mul_f32 v[34:35], v[18:19], v[18:19]
	v_add_f32_e32 v50, v50, v51
	v_add_f32_e32 v35, v50, v35
	v_add_f32_e32 v34, v34, v35
	ds_bpermute_b32 v35, v166, v34
	s_waitcnt lgkmcnt(0)
	v_add_f32_e32 v34, v34, v35
	ds_bpermute_b32 v35, v167, v34
	s_waitcnt lgkmcnt(0)
	v_add_f32_e32 v34, v34, v35
	ds_bpermute_b32 v35, v168, v34
	s_waitcnt lgkmcnt(0)
	v_add_f32_e32 v34, v34, v35
	ds_bpermute_b32 v35, v169, v34
	s_waitcnt lgkmcnt(0)
	v_add_f32_e32 v34, v34, v35
	ds_bpermute_b32 v35, v170, v34
	s_waitcnt lgkmcnt(0)
	v_add_f32_e32 v34, v34, v35
	v_fmamk_f32 v34, v34, 0x3c000000, v249
	v_mul_f32_e32 v35, 0x4b800000, v34
	v_cmp_gt_f32_e32 vcc, s5, v34
	s_nop 1
	v_cndmask_b32_e32 v34, v34, v35, vcc
	v_rsq_f32_e32 v34, v34
	s_nop 0
	v_mul_f32_e32 v35, 0x45800000, v34
	v_cndmask_b32_e32 v34, v34, v35, vcc
	v_mul_f32_e32 v2, v2, v34
	v_mul_f32_e32 v3, v3, v34
	v_mul_f32_e32 v19, v19, v34
	v_mul_f32_e32 v18, v18, v34
	v_mul_f32_e32 v2, v67, v2
	v_mul_f32_e32 v3, v71, v3
	v_mul_f32_e32 v19, v73, v19
	v_mul_f32_e32 v18, v75, v18
	v_cvt_pk_bf16_f32 v2, v2, s0
	v_cvt_pk_bf16_f32 v3, v3, s0
	v_cvt_pk_bf16_f32 v19, v19, s0
	v_cvt_pk_bf16_f32 v18, v18, s0
	ds_write_b16 v76, v2 offset:272
	ds_write_b16 v76, v3 offset:336
	ds_write_b16 v76, v19 offset:400
	ds_write_b16 v76, v18 offset:464
	ds_read2st64_b32 v[2:3], v79 offset0:4 offset1:5
	v_mov_b32_e32 v18, v4
	v_mov_b32_e32 v19, v52
	s_waitcnt lgkmcnt(0)
	v_lshlrev_b32_e32 v34, 16, v2
	v_and_b32_e32 v35, 0xffff0000, v2
	v_lshlrev_b32_e32 v51, 16, v3
	v_and_b32_e32 v50, 0xffff0000, v3
	v_pk_mul_f32 v[2:3], v[18:19], v[96:97] op_sel_hi:[1,0]
	s_nop 0
	v_pk_fma_f32 v[2:3], v[142:143], v[2:3], v[34:35] neg_lo:[1,0,0] neg_hi:[1,0,0]
	v_mov_b32_e32 v34, v36
	v_mov_b32_e32 v35, v20
	v_pk_mul_f32 v[34:35], v[34:35], v[96:97] op_sel_hi:[1,0]
	v_pk_mul_f32 v[18:19], v[2:3], v[2:3]
	v_pk_fma_f32 v[34:35], v[142:143], v[34:35], v[50:51] neg_lo:[1,0,0] neg_hi:[1,0,0]
	v_add_f32_e32 v4, v18, v19
	v_pk_mul_f32 v[50:51], v[34:35], v[34:35]
	s_nop 0
	v_add_f32_e32 v4, v4, v51
	v_add_f32_e32 v4, v50, v4
	ds_bpermute_b32 v18, v166, v4
	s_waitcnt lgkmcnt(0)
	v_add_f32_e32 v4, v4, v18
	ds_bpermute_b32 v18, v167, v4
	s_waitcnt lgkmcnt(0)
	v_add_f32_e32 v4, v4, v18
	ds_bpermute_b32 v18, v168, v4
	s_waitcnt lgkmcnt(0)
	v_add_f32_e32 v4, v4, v18
	ds_bpermute_b32 v18, v169, v4
	s_waitcnt lgkmcnt(0)
	v_add_f32_e32 v4, v4, v18
	ds_bpermute_b32 v18, v170, v4
	s_waitcnt lgkmcnt(0)
	v_add_f32_e32 v4, v4, v18
	v_fmamk_f32 v4, v4, 0x3c000000, v249
	v_mul_f32_e32 v18, 0x4b800000, v4
	v_cmp_gt_f32_e32 vcc, s5, v4
	s_nop 1
	v_cndmask_b32_e32 v4, v4, v18, vcc
	v_rsq_f32_e32 v4, v4
	s_nop 0
	v_mul_f32_e32 v18, 0x45800000, v4
	v_cndmask_b32_e32 v4, v4, v18, vcc
	v_mul_f32_e32 v2, v2, v4
	v_mul_f32_e32 v3, v3, v4
	v_mul_f32_e32 v18, v35, v4
	v_mul_f32_e32 v4, v34, v4
	v_mul_f32_e32 v2, v67, v2
	v_mul_f32_e32 v3, v71, v3
	v_mul_f32_e32 v18, v73, v18
	v_mul_f32_e32 v4, v75, v4
	v_cvt_pk_bf16_f32 v2, v2, s0
	v_cvt_pk_bf16_f32 v3, v3, s0
	v_cvt_pk_bf16_f32 v18, v18, s0
	v_cvt_pk_bf16_f32 v4, v4, s0
	ds_write_b16 v76, v2 offset:544
	ds_write_b16 v76, v3 offset:608
	ds_write_b16 v76, v18 offset:672
	ds_write_b16 v76, v4 offset:736
	ds_read2st64_b32 v[2:3], v79 offset0:6 offset1:7
	v_mov_b32_e32 v52, v5
	v_mov_b32_e32 v20, v37
	s_waitcnt lgkmcnt(0)
	v_lshlrev_b32_e32 v18, 16, v2
	v_and_b32_e32 v19, 0xffff0000, v2
	v_lshlrev_b32_e32 v35, 16, v3
	v_and_b32_e32 v34, 0xffff0000, v3
	v_pk_mul_f32 v[2:3], v[52:53], v[94:95] op_sel_hi:[1,0]
	s_nop 0
	v_pk_fma_f32 v[4:5], v[142:143], v[2:3], v[18:19] neg_lo:[1,0,0] neg_hi:[1,0,0]
	v_pk_mul_f32 v[18:19], v[20:21], v[94:95] op_sel_hi:[1,0]
	v_pk_mul_f32 v[2:3], v[4:5], v[4:5]
	v_pk_fma_f32 v[18:19], v[142:143], v[18:19], v[34:35] neg_lo:[1,0,0] neg_hi:[1,0,0]
	v_add_f32_e32 v2, v2, v3
	v_pk_mul_f32 v[20:21], v[18:19], v[18:19]
	s_nop 0
	v_add_f32_e32 v2, v2, v21
	v_add_f32_e32 v2, v20, v2
	ds_bpermute_b32 v3, v166, v2
	s_waitcnt lgkmcnt(0)
	v_add_f32_e32 v2, v2, v3
	ds_bpermute_b32 v3, v167, v2
	s_waitcnt lgkmcnt(0)
	v_add_f32_e32 v2, v2, v3
	ds_bpermute_b32 v3, v168, v2
	s_waitcnt lgkmcnt(0)
	v_add_f32_e32 v2, v2, v3
	ds_bpermute_b32 v3, v169, v2
	s_waitcnt lgkmcnt(0)
	v_add_f32_e32 v2, v2, v3
	ds_bpermute_b32 v3, v170, v2
	s_waitcnt lgkmcnt(0)
	v_add_f32_e32 v2, v2, v3
	v_fmamk_f32 v2, v2, 0x3c000000, v249
	v_cmp_gt_f32_e32 vcc, s5, v2
	v_mul_f32_e32 v3, 0x4b800000, v2
	s_nop 0
	v_cndmask_b32_e32 v2, v2, v3, vcc
	v_rsq_f32_e32 v2, v2
	s_nop 0
	v_mul_f32_e32 v3, 0x45800000, v2
	v_cndmask_b32_e32 v20, v2, v3, vcc
	v_or_b32_e32 v2, 3, v80
	v_mad_u64_u32 v[2:3], s[22:23], v2, s77, v[78:79]
	v_mul_f32_e32 v3, v4, v20
	v_mul_f32_e32 v3, v67, v3
	v_cvt_pk_bf16_f32 v3, v3, s0
	ds_write_b16 v2, v3
	v_mul_f32_e32 v3, v5, v20
	v_mul_f32_e32 v3, v71, v3
	v_cvt_pk_bf16_f32 v3, v3, s0
	ds_write_b16 v2, v3 offset:64
	v_mul_f32_e32 v3, v19, v20
	v_mul_f32_e32 v3, v73, v3
	v_cvt_pk_bf16_f32 v3, v3, s0
	ds_write_b16 v2, v3 offset:128
	v_mul_f32_e32 v3, v18, v20
	v_mul_f32_e32 v3, v75, v3
	v_cvt_pk_bf16_f32 v3, v3, s0
	ds_write_b16 v2, v3 offset:192
	ds_read2st64_b32 v[4:5], v79 offset0:8 offset1:9
	v_mov_b32_e32 v18, v6
	v_mov_b32_e32 v19, v54
	s_waitcnt lgkmcnt(0)
	v_lshlrev_b32_e32 v20, 16, v4
	v_and_b32_e32 v21, 0xffff0000, v4
	v_lshlrev_b32_e32 v35, 16, v5
	v_and_b32_e32 v34, 0xffff0000, v5
	v_pk_mul_f32 v[4:5], v[18:19], v[92:93] op_sel_hi:[1,0]
	s_nop 0
	v_pk_fma_f32 v[4:5], v[142:143], v[4:5], v[20:21] neg_lo:[1,0,0] neg_hi:[1,0,0]
	v_mov_b32_e32 v20, v38
	v_mov_b32_e32 v21, v22
	v_pk_mul_f32 v[20:21], v[20:21], v[92:93] op_sel_hi:[1,0]
	v_pk_mul_f32 v[18:19], v[4:5], v[4:5]
	v_pk_fma_f32 v[20:21], v[142:143], v[20:21], v[34:35] neg_lo:[1,0,0] neg_hi:[1,0,0]
	v_add_f32_e32 v3, v18, v19
	v_pk_mul_f32 v[34:35], v[20:21], v[20:21]
	s_nop 0
	v_add_f32_e32 v3, v3, v35
	v_add_f32_e32 v3, v34, v3
	ds_bpermute_b32 v6, v166, v3
	s_waitcnt lgkmcnt(0)
	v_add_f32_e32 v3, v3, v6
	ds_bpermute_b32 v6, v167, v3
	s_waitcnt lgkmcnt(0)
	v_add_f32_e32 v3, v3, v6
	ds_bpermute_b32 v6, v168, v3
	s_waitcnt lgkmcnt(0)
	v_add_f32_e32 v3, v3, v6
	ds_bpermute_b32 v6, v169, v3
	s_waitcnt lgkmcnt(0)
	v_add_f32_e32 v3, v3, v6
	ds_bpermute_b32 v6, v170, v3
	s_waitcnt lgkmcnt(0)
	v_add_f32_e32 v3, v3, v6
	v_fmamk_f32 v3, v3, 0x3c000000, v249
	v_mul_f32_e32 v6, 0x4b800000, v3
	v_cmp_gt_f32_e32 vcc, s5, v3
	s_nop 1
	v_cndmask_b32_e32 v3, v3, v6, vcc
	v_rsq_f32_e32 v3, v3
	s_nop 0
	v_mul_f32_e32 v6, 0x45800000, v3
	v_cndmask_b32_e32 v3, v3, v6, vcc
	v_mul_f32_e32 v4, v4, v3
	v_mul_f32_e32 v5, v5, v3
	v_mul_f32_e32 v6, v21, v3
	v_mul_f32_e32 v3, v20, v3
	v_mul_f32_e32 v4, v67, v4
	v_mul_f32_e32 v5, v71, v5
	v_mul_f32_e32 v6, v73, v6
	v_mul_f32_e32 v3, v75, v3
	v_cvt_pk_bf16_f32 v4, v4, s0
	v_cvt_pk_bf16_f32 v5, v5, s0
	v_cvt_pk_bf16_f32 v6, v6, s0
	v_cvt_pk_bf16_f32 v3, v3, s0
	ds_write_b16 v76, v4 offset:2176
	ds_write_b16 v76, v5 offset:2240
	ds_write_b16 v76, v6 offset:2304
	ds_write_b16 v76, v3 offset:2368
	ds_read2st64_b32 v[4:5], v79 offset0:10 offset1:11
	v_mov_b32_e32 v54, v7
	v_mov_b32_e32 v22, v39
	v_pk_mul_f32 v[20:21], v[22:23], v[90:91] op_sel_hi:[1,0]
	s_waitcnt lgkmcnt(0)
	v_lshlrev_b32_e32 v6, 16, v4
	v_and_b32_e32 v7, 0xffff0000, v4
	v_lshlrev_b32_e32 v19, 16, v5
	v_and_b32_e32 v18, 0xffff0000, v5
	v_pk_mul_f32 v[4:5], v[54:55], v[90:91] op_sel_hi:[1,0]
	v_pk_fma_f32 v[18:19], v[142:143], v[20:21], v[18:19] neg_lo:[1,0,0] neg_hi:[1,0,0]
	v_pk_fma_f32 v[4:5], v[142:143], v[4:5], v[6:7] neg_lo:[1,0,0] neg_hi:[1,0,0]
	v_pk_mul_f32 v[20:21], v[18:19], v[18:19]
	v_pk_mul_f32 v[6:7], v[4:5], v[4:5]
	s_nop 0
	v_add_f32_e32 v3, v6, v7
	v_add_f32_e32 v3, v3, v21
	v_add_f32_e32 v3, v20, v3
	ds_bpermute_b32 v6, v166, v3
	s_waitcnt lgkmcnt(0)
	v_add_f32_e32 v3, v3, v6
	ds_bpermute_b32 v6, v167, v3
	s_waitcnt lgkmcnt(0)
	v_add_f32_e32 v3, v3, v6
	ds_bpermute_b32 v6, v168, v3
	s_waitcnt lgkmcnt(0)
	v_add_f32_e32 v3, v3, v6
	ds_bpermute_b32 v6, v169, v3
	s_waitcnt lgkmcnt(0)
	v_add_f32_e32 v3, v3, v6
	ds_bpermute_b32 v6, v170, v3
	s_waitcnt lgkmcnt(0)
	v_add_f32_e32 v3, v3, v6
	v_fmamk_f32 v3, v3, 0x3c000000, v249
	v_mul_f32_e32 v6, 0x4b800000, v3
	v_cmp_gt_f32_e32 vcc, s5, v3
	s_nop 1
	v_cndmask_b32_e32 v3, v3, v6, vcc
	v_rsq_f32_e32 v3, v3
	s_nop 0
	v_mul_f32_e32 v6, 0x45800000, v3
	v_cndmask_b32_e32 v3, v3, v6, vcc
	v_mul_f32_e32 v4, v4, v3
	v_mul_f32_e32 v5, v5, v3
	v_mul_f32_e32 v6, v19, v3
	v_mul_f32_e32 v3, v18, v3
	v_mul_f32_e32 v4, v67, v4
	v_mul_f32_e32 v5, v71, v5
	v_mul_f32_e32 v6, v73, v6
	v_mul_f32_e32 v3, v75, v3
	v_cvt_pk_bf16_f32 v4, v4, s0
	v_cvt_pk_bf16_f32 v5, v5, s0
	v_cvt_pk_bf16_f32 v6, v6, s0
	v_cvt_pk_bf16_f32 v3, v3, s0
	ds_write_b16 v76, v4 offset:2448
	ds_write_b16 v76, v5 offset:2512
	ds_write_b16 v76, v6 offset:2576
	ds_write_b16 v76, v3 offset:2640
	ds_read2st64_b32 v[4:5], v79 offset0:12 offset1:13
	v_mov_b32_e32 v6, v8
	v_mov_b32_e32 v7, v56
	s_waitcnt lgkmcnt(0)
	v_lshlrev_b32_e32 v18, 16, v4
	v_and_b32_e32 v19, 0xffff0000, v4
	v_lshlrev_b32_e32 v21, 16, v5
	v_and_b32_e32 v20, 0xffff0000, v5
	v_pk_mul_f32 v[4:5], v[6:7], v[88:89] op_sel_hi:[1,0]
	s_nop 0
	v_pk_fma_f32 v[4:5], v[142:143], v[4:5], v[18:19] neg_lo:[1,0,0] neg_hi:[1,0,0]
	v_mov_b32_e32 v18, v40
	v_mov_b32_e32 v19, v24
	v_pk_mul_f32 v[18:19], v[18:19], v[88:89] op_sel_hi:[1,0]
	v_pk_mul_f32 v[6:7], v[4:5], v[4:5]
	v_pk_fma_f32 v[18:19], v[142:143], v[18:19], v[20:21] neg_lo:[1,0,0] neg_hi:[1,0,0]
	v_add_f32_e32 v3, v6, v7
	v_pk_mul_f32 v[20:21], v[18:19], v[18:19]
	s_nop 0
	v_add_f32_e32 v3, v3, v21
	v_add_f32_e32 v3, v20, v3
	ds_bpermute_b32 v6, v166, v3
	s_waitcnt lgkmcnt(0)
	v_add_f32_e32 v3, v3, v6
	ds_bpermute_b32 v6, v167, v3
	s_waitcnt lgkmcnt(0)
	v_add_f32_e32 v3, v3, v6
	ds_bpermute_b32 v6, v168, v3
	s_waitcnt lgkmcnt(0)
	v_add_f32_e32 v3, v3, v6
	ds_bpermute_b32 v6, v169, v3
	s_waitcnt lgkmcnt(0)
	v_add_f32_e32 v3, v3, v6
	ds_bpermute_b32 v6, v170, v3
	s_waitcnt lgkmcnt(0)
	v_add_f32_e32 v3, v3, v6
	v_fmamk_f32 v3, v3, 0x3c000000, v249
	v_mul_f32_e32 v6, 0x4b800000, v3
	v_cmp_gt_f32_e32 vcc, s5, v3
	s_nop 1
	v_cndmask_b32_e32 v3, v3, v6, vcc
	v_rsq_f32_e32 v3, v3
	s_nop 0
	v_mul_f32_e32 v6, 0x45800000, v3
	v_cndmask_b32_e32 v3, v3, v6, vcc
	v_mul_f32_e32 v4, v4, v3
	v_mul_f32_e32 v5, v5, v3
	v_mul_f32_e32 v6, v19, v3
	v_mul_f32_e32 v3, v18, v3
	v_mul_f32_e32 v4, v67, v4
	v_mul_f32_e32 v5, v71, v5
	v_mul_f32_e32 v6, v73, v6
	v_mul_f32_e32 v3, v75, v3
	v_cvt_pk_bf16_f32 v4, v4, s0
	v_cvt_pk_bf16_f32 v5, v5, s0
	v_cvt_pk_bf16_f32 v6, v6, s0
	v_cvt_pk_bf16_f32 v3, v3, s0
	ds_write_b16 v76, v4 offset:2720
	ds_write_b16 v76, v5 offset:2784
	ds_write_b16 v76, v6 offset:2848
	ds_write_b16 v76, v3 offset:2912
	ds_read2st64_b32 v[4:5], v79 offset0:14 offset1:15
	v_mov_b32_e32 v56, v9
	v_mov_b32_e32 v24, v41
	v_pk_mul_f32 v[18:19], v[24:25], v[86:87] op_sel_hi:[1,0]
	s_waitcnt lgkmcnt(0)
	v_lshlrev_b32_e32 v6, 16, v4
	v_and_b32_e32 v7, 0xffff0000, v4
	v_lshlrev_b32_e32 v9, 16, v5
	v_and_b32_e32 v8, 0xffff0000, v5
	v_pk_mul_f32 v[4:5], v[56:57], v[86:87] op_sel_hi:[1,0]
	v_pk_fma_f32 v[8:9], v[142:143], v[18:19], v[8:9] neg_lo:[1,0,0] neg_hi:[1,0,0]
	v_pk_fma_f32 v[4:5], v[142:143], v[4:5], v[6:7] neg_lo:[1,0,0] neg_hi:[1,0,0]
	v_pk_mul_f32 v[18:19], v[8:9], v[8:9]
	v_pk_mul_f32 v[6:7], v[4:5], v[4:5]
	s_nop 0
	v_add_f32_e32 v3, v6, v7
	v_add_f32_e32 v3, v3, v19
	v_add_f32_e32 v3, v18, v3
	ds_bpermute_b32 v6, v166, v3
	s_waitcnt lgkmcnt(0)
	v_add_f32_e32 v3, v3, v6
	ds_bpermute_b32 v6, v167, v3
	s_waitcnt lgkmcnt(0)
	v_add_f32_e32 v3, v3, v6
	ds_bpermute_b32 v6, v168, v3
	s_waitcnt lgkmcnt(0)
	v_add_f32_e32 v3, v3, v6
	ds_bpermute_b32 v6, v169, v3
	s_waitcnt lgkmcnt(0)
	v_add_f32_e32 v3, v3, v6
	ds_bpermute_b32 v6, v170, v3
	s_waitcnt lgkmcnt(0)
	v_add_f32_e32 v3, v3, v6
	v_fmamk_f32 v3, v3, 0x3c000000, v249
	v_mul_f32_e32 v6, 0x4b800000, v3
	v_cmp_gt_f32_e32 vcc, s5, v3
	s_nop 1
	v_cndmask_b32_e32 v3, v3, v6, vcc
	v_rsq_f32_e32 v3, v3
	s_nop 0
	v_mul_f32_e32 v6, 0x45800000, v3
	v_cndmask_b32_e32 v3, v3, v6, vcc
	v_mul_f32_e32 v4, v4, v3
	v_mul_f32_e32 v5, v5, v3
	v_mul_f32_e32 v6, v9, v3
	v_mul_f32_e32 v3, v8, v3
	v_mul_f32_e32 v4, v67, v4
	v_mul_f32_e32 v5, v71, v5
	v_mul_f32_e32 v6, v73, v6
	v_mul_f32_e32 v3, v75, v3
	v_cvt_pk_bf16_f32 v4, v4, s0
	v_cvt_pk_bf16_f32 v5, v5, s0
	v_cvt_pk_bf16_f32 v6, v6, s0
	v_cvt_pk_bf16_f32 v3, v3, s0
	ds_write_b16 v2, v4 offset:2176
	ds_write_b16 v2, v5 offset:2240
	ds_write_b16 v2, v6 offset:2304
	ds_write_b16 v2, v3 offset:2368
	ds_read2st64_b32 v[4:5], v79 offset0:16 offset1:17
	v_mov_b32_e32 v6, v10
	v_mov_b32_e32 v7, v58
	s_waitcnt lgkmcnt(0)
	v_lshlrev_b32_e32 v8, 16, v4
	v_and_b32_e32 v9, 0xffff0000, v4
	v_lshlrev_b32_e32 v19, 16, v5
	v_and_b32_e32 v18, 0xffff0000, v5
	v_pk_mul_f32 v[4:5], v[6:7], v[84:85] op_sel_hi:[1,0]
	s_nop 0
	v_pk_fma_f32 v[4:5], v[142:143], v[4:5], v[8:9] neg_lo:[1,0,0] neg_hi:[1,0,0]
	v_mov_b32_e32 v8, v42
	v_mov_b32_e32 v9, v26
	v_pk_mul_f32 v[8:9], v[8:9], v[84:85] op_sel_hi:[1,0]
	v_pk_mul_f32 v[6:7], v[4:5], v[4:5]
	v_pk_fma_f32 v[8:9], v[142:143], v[8:9], v[18:19] neg_lo:[1,0,0] neg_hi:[1,0,0]
	v_add_f32_e32 v3, v6, v7
	v_pk_mul_f32 v[18:19], v[8:9], v[8:9]
	s_nop 0
	v_add_f32_e32 v3, v3, v19
	v_add_f32_e32 v3, v18, v3
	ds_bpermute_b32 v6, v166, v3
	s_waitcnt lgkmcnt(0)
	v_add_f32_e32 v3, v3, v6
	ds_bpermute_b32 v6, v167, v3
	s_waitcnt lgkmcnt(0)
	v_add_f32_e32 v3, v3, v6
	ds_bpermute_b32 v6, v168, v3
	s_waitcnt lgkmcnt(0)
	v_add_f32_e32 v3, v3, v6
	ds_bpermute_b32 v6, v169, v3
	s_waitcnt lgkmcnt(0)
	v_add_f32_e32 v3, v3, v6
	ds_bpermute_b32 v6, v170, v3
	s_waitcnt lgkmcnt(0)
	v_add_f32_e32 v3, v3, v6
	v_fmamk_f32 v3, v3, 0x3c000000, v249
	v_mul_f32_e32 v6, 0x4b800000, v3
	v_cmp_gt_f32_e32 vcc, s5, v3
	s_nop 1
	v_cndmask_b32_e32 v3, v3, v6, vcc
	v_rsq_f32_e32 v3, v3
	s_nop 0
	v_mul_f32_e32 v6, 0x45800000, v3
	v_cndmask_b32_e32 v3, v3, v6, vcc
	v_mul_f32_e32 v4, v4, v3
	v_mul_f32_e32 v5, v5, v3
	v_mul_f32_e32 v6, v9, v3
	v_mul_f32_e32 v3, v8, v3
	v_mul_f32_e32 v4, v67, v4
	v_mul_f32_e32 v5, v71, v5
	v_mul_f32_e32 v6, v73, v6
	v_mul_f32_e32 v3, v75, v3
	v_cvt_pk_bf16_f32 v4, v4, s0
	v_cvt_pk_bf16_f32 v5, v5, s0
	v_cvt_pk_bf16_f32 v6, v6, s0
	v_cvt_pk_bf16_f32 v3, v3, s0
	ds_write_b16 v76, v4 offset:4352
	ds_write_b16 v76, v5 offset:4416
	ds_write_b16 v76, v6 offset:4480
	ds_write_b16 v76, v3 offset:4544
	ds_read2st64_b32 v[4:5], v79 offset0:18 offset1:19
	v_mov_b32_e32 v58, v11
	v_mov_b32_e32 v26, v43
	v_pk_mul_f32 v[10:11], v[26:27], v[82:83] op_sel_hi:[1,0]
	s_waitcnt lgkmcnt(0)
	v_lshlrev_b32_e32 v6, 16, v4
	v_and_b32_e32 v7, 0xffff0000, v4
	v_lshlrev_b32_e32 v9, 16, v5
	v_and_b32_e32 v8, 0xffff0000, v5
	v_pk_mul_f32 v[4:5], v[58:59], v[82:83] op_sel_hi:[1,0]
	v_pk_fma_f32 v[8:9], v[142:143], v[10:11], v[8:9] neg_lo:[1,0,0] neg_hi:[1,0,0]
	v_pk_fma_f32 v[4:5], v[142:143], v[4:5], v[6:7] neg_lo:[1,0,0] neg_hi:[1,0,0]
	v_pk_mul_f32 v[10:11], v[8:9], v[8:9]
	v_pk_mul_f32 v[6:7], v[4:5], v[4:5]
	s_nop 0
	v_add_f32_e32 v3, v6, v7
	v_add_f32_e32 v3, v3, v11
	v_add_f32_e32 v3, v10, v3
	ds_bpermute_b32 v6, v166, v3
	s_waitcnt lgkmcnt(0)
	v_add_f32_e32 v3, v3, v6
	ds_bpermute_b32 v6, v167, v3
	s_waitcnt lgkmcnt(0)
	v_add_f32_e32 v3, v3, v6
	ds_bpermute_b32 v6, v168, v3
	s_waitcnt lgkmcnt(0)
	v_add_f32_e32 v3, v3, v6
	ds_bpermute_b32 v6, v169, v3
	s_waitcnt lgkmcnt(0)
	v_add_f32_e32 v3, v3, v6
	ds_bpermute_b32 v6, v170, v3
	s_waitcnt lgkmcnt(0)
	v_add_f32_e32 v3, v3, v6
	v_fmamk_f32 v3, v3, 0x3c000000, v249
	v_mul_f32_e32 v6, 0x4b800000, v3
	v_cmp_gt_f32_e32 vcc, s5, v3
	s_nop 1
	v_cndmask_b32_e32 v3, v3, v6, vcc
	v_rsq_f32_e32 v3, v3
	s_nop 0
	v_mul_f32_e32 v6, 0x45800000, v3
	v_cndmask_b32_e32 v3, v3, v6, vcc
	v_mul_f32_e32 v4, v4, v3
	v_mul_f32_e32 v5, v5, v3
	v_mul_f32_e32 v6, v9, v3
	v_mul_f32_e32 v3, v8, v3
	v_mul_f32_e32 v4, v67, v4
	v_mul_f32_e32 v5, v71, v5
	v_mul_f32_e32 v6, v73, v6
	v_mul_f32_e32 v3, v75, v3
	v_cvt_pk_bf16_f32 v4, v4, s0
	v_cvt_pk_bf16_f32 v5, v5, s0
	v_cvt_pk_bf16_f32 v6, v6, s0
	v_cvt_pk_bf16_f32 v3, v3, s0
	ds_write_b16 v76, v4 offset:4624
	ds_write_b16 v76, v5 offset:4688
	ds_write_b16 v76, v6 offset:4752
	ds_write_b16 v76, v3 offset:4816
	ds_read2st64_b32 v[4:5], v79 offset0:20 offset1:21
	v_mov_b32_e32 v6, v12
	v_mov_b32_e32 v7, v60
	s_waitcnt lgkmcnt(0)
	v_lshlrev_b32_e32 v8, 16, v4
	v_and_b32_e32 v9, 0xffff0000, v4
	v_lshlrev_b32_e32 v11, 16, v5
	v_and_b32_e32 v10, 0xffff0000, v5
	v_pk_mul_f32 v[4:5], v[6:7], v[74:75] op_sel_hi:[1,0]
	s_nop 0
	v_pk_fma_f32 v[4:5], v[142:143], v[4:5], v[8:9] neg_lo:[1,0,0] neg_hi:[1,0,0]
	v_mov_b32_e32 v8, v44
	v_mov_b32_e32 v9, v28
	v_pk_mul_f32 v[8:9], v[8:9], v[74:75] op_sel_hi:[1,0]
	v_pk_mul_f32 v[6:7], v[4:5], v[4:5]
	v_pk_fma_f32 v[8:9], v[142:143], v[8:9], v[10:11] neg_lo:[1,0,0] neg_hi:[1,0,0]
	v_add_f32_e32 v3, v6, v7
	v_pk_mul_f32 v[10:11], v[8:9], v[8:9]
	s_nop 0
	v_add_f32_e32 v3, v3, v11
	v_add_f32_e32 v3, v10, v3
	ds_bpermute_b32 v6, v166, v3
	s_waitcnt lgkmcnt(0)
	v_add_f32_e32 v3, v3, v6
	ds_bpermute_b32 v6, v167, v3
	s_waitcnt lgkmcnt(0)
	v_add_f32_e32 v3, v3, v6
	ds_bpermute_b32 v6, v168, v3
	s_waitcnt lgkmcnt(0)
	v_add_f32_e32 v3, v3, v6
	ds_bpermute_b32 v6, v169, v3
	s_waitcnt lgkmcnt(0)
	v_add_f32_e32 v3, v3, v6
	ds_bpermute_b32 v6, v170, v3
	s_waitcnt lgkmcnt(0)
	v_add_f32_e32 v3, v3, v6
	v_fmamk_f32 v3, v3, 0x3c000000, v249
	v_mul_f32_e32 v6, 0x4b800000, v3
	v_cmp_gt_f32_e32 vcc, s5, v3
	s_nop 1
	v_cndmask_b32_e32 v3, v3, v6, vcc
	v_rsq_f32_e32 v3, v3
	s_nop 0
	v_mul_f32_e32 v6, 0x45800000, v3
	v_cndmask_b32_e32 v3, v3, v6, vcc
	v_mul_f32_e32 v4, v4, v3
	v_mul_f32_e32 v5, v5, v3
	v_mul_f32_e32 v6, v9, v3
	v_mul_f32_e32 v3, v8, v3
	v_mul_f32_e32 v4, v67, v4
	v_mul_f32_e32 v5, v71, v5
	v_mul_f32_e32 v6, v73, v6
	v_mul_f32_e32 v3, v75, v3
	v_cvt_pk_bf16_f32 v4, v4, s0
	v_cvt_pk_bf16_f32 v5, v5, s0
	v_cvt_pk_bf16_f32 v6, v6, s0
	v_cvt_pk_bf16_f32 v3, v3, s0
	ds_write_b16 v76, v4 offset:4896
	ds_write_b16 v76, v5 offset:4960
	ds_write_b16 v76, v6 offset:5024
	ds_write_b16 v76, v3 offset:5088
	ds_read2st64_b32 v[4:5], v79 offset0:22 offset1:23
	v_mov_b32_e32 v60, v13
	v_mov_b32_e32 v28, v45
	v_pk_mul_f32 v[10:11], v[28:29], v[72:73] op_sel_hi:[1,0]
	s_waitcnt lgkmcnt(0)
	v_lshlrev_b32_e32 v6, 16, v4
	v_and_b32_e32 v7, 0xffff0000, v4
	v_lshlrev_b32_e32 v9, 16, v5
	v_and_b32_e32 v8, 0xffff0000, v5
	v_pk_mul_f32 v[4:5], v[60:61], v[72:73] op_sel_hi:[1,0]
	v_pk_fma_f32 v[8:9], v[142:143], v[10:11], v[8:9] neg_lo:[1,0,0] neg_hi:[1,0,0]
	v_pk_fma_f32 v[4:5], v[142:143], v[4:5], v[6:7] neg_lo:[1,0,0] neg_hi:[1,0,0]
	v_pk_mul_f32 v[10:11], v[8:9], v[8:9]
	v_pk_mul_f32 v[6:7], v[4:5], v[4:5]
	s_nop 0
	v_add_f32_e32 v3, v6, v7
	v_add_f32_e32 v3, v3, v11
	v_add_f32_e32 v3, v10, v3
	ds_bpermute_b32 v6, v166, v3
	s_waitcnt lgkmcnt(0)
	v_add_f32_e32 v3, v3, v6
	ds_bpermute_b32 v6, v167, v3
	s_waitcnt lgkmcnt(0)
	v_add_f32_e32 v3, v3, v6
	ds_bpermute_b32 v6, v168, v3
	s_waitcnt lgkmcnt(0)
	v_add_f32_e32 v3, v3, v6
	ds_bpermute_b32 v6, v169, v3
	s_waitcnt lgkmcnt(0)
	v_add_f32_e32 v3, v3, v6
	ds_bpermute_b32 v6, v170, v3
	s_waitcnt lgkmcnt(0)
	v_add_f32_e32 v3, v3, v6
	v_fmamk_f32 v3, v3, 0x3c000000, v249
	v_mul_f32_e32 v6, 0x4b800000, v3
	v_cmp_gt_f32_e32 vcc, s5, v3
	s_nop 1
	v_cndmask_b32_e32 v3, v3, v6, vcc
	v_rsq_f32_e32 v3, v3
	s_nop 0
	v_mul_f32_e32 v6, 0x45800000, v3
	v_cndmask_b32_e32 v3, v3, v6, vcc
	v_mul_f32_e32 v4, v4, v3
	v_mul_f32_e32 v5, v5, v3
	v_mul_f32_e32 v6, v9, v3
	v_mul_f32_e32 v3, v8, v3
	v_mul_f32_e32 v4, v67, v4
	v_mul_f32_e32 v5, v71, v5
	v_mul_f32_e32 v6, v73, v6
	v_mul_f32_e32 v3, v75, v3
	v_cvt_pk_bf16_f32 v4, v4, s0
	v_cvt_pk_bf16_f32 v5, v5, s0
	v_cvt_pk_bf16_f32 v6, v6, s0
	v_cvt_pk_bf16_f32 v3, v3, s0
	ds_write_b16 v2, v4 offset:4352
	ds_write_b16 v2, v5 offset:4416
	ds_write_b16 v2, v6 offset:4480
	ds_write_b16 v2, v3 offset:4544
	ds_read2st64_b32 v[4:5], v79 offset0:24 offset1:25
	v_mov_b32_e32 v6, v14
	v_mov_b32_e32 v7, v62
	s_waitcnt lgkmcnt(0)
	v_lshlrev_b32_e32 v8, 16, v4
	v_and_b32_e32 v9, 0xffff0000, v4
	v_lshlrev_b32_e32 v11, 16, v5
	v_and_b32_e32 v10, 0xffff0000, v5
	v_pk_mul_f32 v[4:5], v[6:7], v[70:71] op_sel_hi:[1,0]
	s_nop 0
	v_pk_fma_f32 v[4:5], v[142:143], v[4:5], v[8:9] neg_lo:[1,0,0] neg_hi:[1,0,0]
	v_mov_b32_e32 v8, v46
	v_mov_b32_e32 v9, v30
	v_pk_mul_f32 v[8:9], v[8:9], v[70:71] op_sel_hi:[1,0]
	v_pk_mul_f32 v[6:7], v[4:5], v[4:5]
	v_pk_fma_f32 v[8:9], v[142:143], v[8:9], v[10:11] neg_lo:[1,0,0] neg_hi:[1,0,0]
	v_add_f32_e32 v3, v6, v7
	v_pk_mul_f32 v[10:11], v[8:9], v[8:9]
	s_nop 0
	v_add_f32_e32 v3, v3, v11
	v_add_f32_e32 v3, v10, v3
	ds_bpermute_b32 v6, v166, v3
	s_waitcnt lgkmcnt(0)
	v_add_f32_e32 v3, v3, v6
	ds_bpermute_b32 v6, v167, v3
	s_waitcnt lgkmcnt(0)
	v_add_f32_e32 v3, v3, v6
	ds_bpermute_b32 v6, v168, v3
	s_waitcnt lgkmcnt(0)
	v_add_f32_e32 v3, v3, v6
	ds_bpermute_b32 v6, v169, v3
	s_waitcnt lgkmcnt(0)
	v_add_f32_e32 v3, v3, v6
	ds_bpermute_b32 v6, v170, v3
	s_waitcnt lgkmcnt(0)
	v_add_f32_e32 v3, v3, v6
	v_fmamk_f32 v3, v3, 0x3c000000, v249
	v_mul_f32_e32 v6, 0x4b800000, v3
	v_cmp_gt_f32_e32 vcc, s5, v3
	s_nop 1
	v_cndmask_b32_e32 v3, v3, v6, vcc
	v_rsq_f32_e32 v3, v3
	s_nop 0
	v_mul_f32_e32 v6, 0x45800000, v3
	v_cndmask_b32_e32 v3, v3, v6, vcc
	v_mul_f32_e32 v4, v4, v3
	v_mul_f32_e32 v5, v5, v3
	v_mul_f32_e32 v6, v9, v3
	v_mul_f32_e32 v3, v8, v3
	v_mul_f32_e32 v4, v67, v4
	v_mul_f32_e32 v5, v71, v5
	v_mul_f32_e32 v6, v73, v6
	v_mul_f32_e32 v3, v75, v3
	v_cvt_pk_bf16_f32 v4, v4, s0
	v_cvt_pk_bf16_f32 v5, v5, s0
	v_cvt_pk_bf16_f32 v6, v6, s0
	v_cvt_pk_bf16_f32 v3, v3, s0
	ds_write_b16 v76, v4 offset:6528
	ds_write_b16 v76, v5 offset:6592
	ds_write_b16 v76, v6 offset:6656
	ds_write_b16 v76, v3 offset:6720
	ds_read2st64_b32 v[4:5], v79 offset0:26 offset1:27
	v_mov_b32_e32 v62, v15
	v_mov_b32_e32 v30, v47
	v_pk_mul_f32 v[10:11], v[30:31], v[68:69] op_sel_hi:[1,0]
	s_waitcnt lgkmcnt(0)
	v_lshlrev_b32_e32 v6, 16, v4
	v_and_b32_e32 v7, 0xffff0000, v4
	v_lshlrev_b32_e32 v9, 16, v5
	v_and_b32_e32 v8, 0xffff0000, v5
	v_pk_mul_f32 v[4:5], v[62:63], v[68:69] op_sel_hi:[1,0]
	v_pk_fma_f32 v[8:9], v[142:143], v[10:11], v[8:9] neg_lo:[1,0,0] neg_hi:[1,0,0]
	v_pk_fma_f32 v[4:5], v[142:143], v[4:5], v[6:7] neg_lo:[1,0,0] neg_hi:[1,0,0]
	v_pk_mul_f32 v[10:11], v[8:9], v[8:9]
	v_pk_mul_f32 v[6:7], v[4:5], v[4:5]
	s_nop 0
	v_add_f32_e32 v3, v6, v7
	v_add_f32_e32 v3, v3, v11
	v_add_f32_e32 v3, v10, v3
	ds_bpermute_b32 v6, v166, v3
	s_waitcnt lgkmcnt(0)
	v_add_f32_e32 v3, v3, v6
	ds_bpermute_b32 v6, v167, v3
	s_waitcnt lgkmcnt(0)
	v_add_f32_e32 v3, v3, v6
	ds_bpermute_b32 v6, v168, v3
	s_waitcnt lgkmcnt(0)
	v_add_f32_e32 v3, v3, v6
	ds_bpermute_b32 v6, v169, v3
	s_waitcnt lgkmcnt(0)
	v_add_f32_e32 v3, v3, v6
	ds_bpermute_b32 v6, v170, v3
	s_waitcnt lgkmcnt(0)
	v_add_f32_e32 v3, v3, v6
	v_fmamk_f32 v3, v3, 0x3c000000, v249
	v_mul_f32_e32 v6, 0x4b800000, v3
	v_cmp_gt_f32_e32 vcc, s5, v3
	s_nop 1
	v_cndmask_b32_e32 v3, v3, v6, vcc
	v_rsq_f32_e32 v3, v3
	s_nop 0
	v_mul_f32_e32 v6, 0x45800000, v3
	v_cndmask_b32_e32 v3, v3, v6, vcc
	v_mul_f32_e32 v4, v4, v3
	v_mul_f32_e32 v5, v5, v3
	v_mul_f32_e32 v6, v9, v3
	v_mul_f32_e32 v3, v8, v3
	v_mul_f32_e32 v4, v67, v4
	v_mul_f32_e32 v5, v71, v5
	v_mul_f32_e32 v6, v73, v6
	v_mul_f32_e32 v3, v75, v3
	v_cvt_pk_bf16_f32 v4, v4, s0
	v_cvt_pk_bf16_f32 v5, v5, s0
	v_cvt_pk_bf16_f32 v6, v6, s0
	v_cvt_pk_bf16_f32 v3, v3, s0
	ds_write_b16 v76, v4 offset:6800
	ds_write_b16 v76, v5 offset:6864
	ds_write_b16 v76, v6 offset:6928
	ds_write_b16 v76, v3 offset:6992
	ds_read2st64_b32 v[4:5], v79 offset0:28 offset1:29
	v_mov_b32_e32 v6, v16
	v_mov_b32_e32 v7, v64
	s_waitcnt lgkmcnt(0)
	v_lshlrev_b32_e32 v8, 16, v4
	v_and_b32_e32 v9, 0xffff0000, v4
	v_lshlrev_b32_e32 v11, 16, v5
	v_and_b32_e32 v10, 0xffff0000, v5
	v_pk_mul_f32 v[4:5], v[6:7], v[66:67] op_sel_hi:[1,0]
	s_nop 0
	v_pk_fma_f32 v[4:5], v[142:143], v[4:5], v[8:9] neg_lo:[1,0,0] neg_hi:[1,0,0]
	v_mov_b32_e32 v8, v48
	v_mov_b32_e32 v9, v32
	v_pk_mul_f32 v[8:9], v[8:9], v[66:67] op_sel_hi:[1,0]
	v_pk_mul_f32 v[6:7], v[4:5], v[4:5]
	v_pk_fma_f32 v[8:9], v[142:143], v[8:9], v[10:11] neg_lo:[1,0,0] neg_hi:[1,0,0]
	v_add_f32_e32 v3, v6, v7
	v_pk_mul_f32 v[10:11], v[8:9], v[8:9]
	s_nop 0
	v_add_f32_e32 v3, v3, v11
	v_add_f32_e32 v3, v10, v3
	ds_bpermute_b32 v6, v166, v3
	s_waitcnt lgkmcnt(0)
	v_add_f32_e32 v3, v3, v6
	ds_bpermute_b32 v6, v167, v3
	s_waitcnt lgkmcnt(0)
	v_add_f32_e32 v3, v3, v6
	ds_bpermute_b32 v6, v168, v3
	s_waitcnt lgkmcnt(0)
	v_add_f32_e32 v3, v3, v6
	ds_bpermute_b32 v6, v169, v3
	s_waitcnt lgkmcnt(0)
	v_add_f32_e32 v3, v3, v6
	ds_bpermute_b32 v6, v170, v3
	s_waitcnt lgkmcnt(0)
	v_add_f32_e32 v3, v3, v6
	v_fmamk_f32 v3, v3, 0x3c000000, v249
	v_mul_f32_e32 v6, 0x4b800000, v3
	v_cmp_gt_f32_e32 vcc, s5, v3
	s_nop 1
	v_cndmask_b32_e32 v3, v3, v6, vcc
	v_rsq_f32_e32 v3, v3
	s_nop 0
	v_mul_f32_e32 v6, 0x45800000, v3
	v_cndmask_b32_e32 v3, v3, v6, vcc
	v_mul_f32_e32 v4, v4, v3
	v_mul_f32_e32 v5, v5, v3
	v_mul_f32_e32 v6, v9, v3
	v_mul_f32_e32 v3, v8, v3
	v_mul_f32_e32 v4, v67, v4
	v_mul_f32_e32 v5, v71, v5
	v_mul_f32_e32 v6, v73, v6
	v_mul_f32_e32 v3, v75, v3
	v_cvt_pk_bf16_f32 v4, v4, s0
	v_cvt_pk_bf16_f32 v5, v5, s0
	v_cvt_pk_bf16_f32 v6, v6, s0
	v_cvt_pk_bf16_f32 v3, v3, s0
	ds_write_b16 v76, v4 offset:7072
	ds_write_b16 v76, v5 offset:7136
	ds_write_b16 v76, v6 offset:7200
	ds_write_b16 v76, v3 offset:7264
	ds_read2st64_b32 v[4:5], v79 offset0:30 offset1:31
	v_mov_b32_e32 v64, v17
	v_mov_b32_e32 v32, v49
	v_pk_mul_f32 v[10:11], v[32:33], v[0:1] op_sel_hi:[1,0]
	s_waitcnt lgkmcnt(0)
	v_lshlrev_b32_e32 v6, 16, v4
	v_and_b32_e32 v7, 0xffff0000, v4
	v_lshlrev_b32_e32 v9, 16, v5
	v_and_b32_e32 v8, 0xffff0000, v5
	v_pk_mul_f32 v[4:5], v[64:65], v[0:1] op_sel_hi:[1,0]
	v_pk_fma_f32 v[8:9], v[142:143], v[10:11], v[8:9] neg_lo:[1,0,0] neg_hi:[1,0,0]
	v_pk_fma_f32 v[4:5], v[142:143], v[4:5], v[6:7] neg_lo:[1,0,0] neg_hi:[1,0,0]
	v_pk_mul_f32 v[10:11], v[8:9], v[8:9]
	v_pk_mul_f32 v[6:7], v[4:5], v[4:5]
	s_nop 0
	v_add_f32_e32 v0, v6, v7
	v_add_f32_e32 v0, v0, v11
	v_add_f32_e32 v0, v10, v0
	ds_bpermute_b32 v3, v166, v0
	s_waitcnt lgkmcnt(0)
	v_add_f32_e32 v0, v0, v3
	ds_bpermute_b32 v3, v167, v0
	s_waitcnt lgkmcnt(0)
	v_add_f32_e32 v0, v0, v3
	ds_bpermute_b32 v3, v168, v0
	s_waitcnt lgkmcnt(0)
	v_add_f32_e32 v0, v0, v3
	ds_bpermute_b32 v3, v169, v0
	s_waitcnt lgkmcnt(0)
	v_add_f32_e32 v0, v0, v3
	ds_bpermute_b32 v3, v170, v0
	s_waitcnt lgkmcnt(0)
	v_add_f32_e32 v0, v0, v3
	v_fmamk_f32 v0, v0, 0x3c000000, v249
	v_mul_f32_e32 v3, 0x4b800000, v0
	v_cmp_gt_f32_e32 vcc, s5, v0
	s_nop 1
	v_cndmask_b32_e32 v0, v0, v3, vcc
	v_rsq_f32_e32 v0, v0
	s_nop 0
	v_mul_f32_e32 v3, 0x45800000, v0
	v_cndmask_b32_e32 v0, v0, v3, vcc
	v_mul_f32_e32 v3, v4, v0
	v_mul_f32_e32 v4, v5, v0
	v_mul_f32_e32 v5, v9, v0
	v_mul_f32_e32 v0, v8, v0
	v_mul_f32_e32 v3, v67, v3
	v_mul_f32_e32 v4, v71, v4
	v_mul_f32_e32 v5, v73, v5
	v_mul_f32_e32 v0, v75, v0
	v_cvt_pk_bf16_f32 v3, v3, s0
	v_cvt_pk_bf16_f32 v4, v4, s0
	v_cvt_pk_bf16_f32 v5, v5, s0
	v_cvt_pk_bf16_f32 v0, v0, s0
	ds_write_b16 v2, v3 offset:6528
	ds_write_b16 v2, v4 offset:6592
	ds_write_b16 v2, v5 offset:6656
	ds_write_b16 v2, v0 offset:6720
	s_lshl_b32 s60, s70, 12
	s_add_i32 s22, s1, s60
	s_ashr_i32 s23, s22, 31
	s_lshl_b64 s[22:23], s[22:23], 11
	s_add_u32 s1, s41, s22
	s_addc_u32 s5, s66, s23
	s_lshl_b32 s61, s71, 1
	s_add_u32 s22, s1, s61
	v_ashrrev_i32_e32 v6, 4, v162
	v_lshlrev_b32_e32 v0, 4, v162
	s_addc_u32 s23, s5, 0
	v_and_b32_e32 v0, 0xf0, v0
	v_mul_lo_u32 v2, v6, s77
	s_waitcnt lgkmcnt(0)
	v_lshl_add_u64 v[8:9], s[22:23], 0, v[0:1]
	v_add3_u32 v0, v69, v0, v2
	ds_read_b128 v[2:5], v0
	v_ashrrev_i32_e32 v7, 31, v6
	v_lshlrev_b64 v[6:7], 11, v[6:7]
	v_lshl_add_u64 v[10:11], v[8:9], 0, v[6:7]
	ds_read_b128 v[6:9], v0 offset:1088
	s_waitcnt lgkmcnt(1)
	global_store_dwordx4 v[10:11], v[2:5], off
	v_mov_b32_e32 v172, v226
	s_movk_i32 s26, 0x1800
	v_add_co_u32_e32 v2, vcc, s88, v10
	v_mov_b32_e32 v145, v1
	s_nop 0
	v_addc_co_u32_e32 v3, vcc, 0, v11, vcc
	s_waitcnt lgkmcnt(0)
	global_store_dwordx4 v[2:3], v[6:9], off
	ds_read_b128 v[2:5], v0 offset:2176
	ds_read_b128 v[6:9], v0 offset:3264
	v_add_co_u32_e32 v12, vcc, s14, v10
	v_readlane_b32 s1, v251, 7
	s_nop 0
	v_addc_co_u32_e32 v13, vcc, 0, v11, vcc
	s_waitcnt lgkmcnt(1)
	global_store_dwordx4 v[12:13], v[2:5], off
	s_add_i32 s1, s11, s1
	v_mov_b32_e32 v16, v1
	v_add_co_u32_e32 v2, vcc, s89, v10
	v_mov_b32_e32 v17, v1
	s_nop 0
	v_addc_co_u32_e32 v3, vcc, 0, v11, vcc
	s_waitcnt lgkmcnt(0)
	global_store_dwordx4 v[2:3], v[6:9], off
	ds_read_b128 v[2:5], v0 offset:4352
	ds_read_b128 v[6:9], v0 offset:5440
	v_add_co_u32_e32 v12, vcc, s81, v10
	s_add_i32 s5, s11, 0x100
	s_nop 0
	v_addc_co_u32_e32 v13, vcc, 0, v11, vcc
	s_waitcnt lgkmcnt(1)
	global_store_dwordx4 v[12:13], v[2:5], off
	v_mov_b32_e32 v14, v1
	v_mov_b32_e32 v15, v1
	v_add_co_u32_e32 v2, vcc, s20, v10
	s_lshr_b32 s5, s5, 6
	s_nop 0
	v_addc_co_u32_e32 v3, vcc, 0, v11, vcc
	s_waitcnt lgkmcnt(0)
	global_store_dwordx4 v[2:3], v[6:9], off
	ds_read_b128 v[2:5], v0 offset:6528
	ds_read_b128 v[6:9], v0 offset:7616
	v_add_co_u32_e32 v12, vcc, s18, v10
	s_or_b32 s11, s1, 31
	s_nop 0
	v_addc_co_u32_e32 v13, vcc, 0, v11, vcc
	s_waitcnt lgkmcnt(1)
	global_store_dwordx4 v[12:13], v[2:5], off
	v_mov_b32_e32 v12, v1
	v_mov_b32_e32 v13, v1
	v_add_co_u32_e32 v2, vcc, s3, v10
	v_mov_b32_e32 v243, 0xff800000
	s_nop 0
	v_addc_co_u32_e32 v3, vcc, 0, v11, vcc
	s_waitcnt lgkmcnt(0)
	global_store_dwordx4 v[2:3], v[6:9], off
	s_barrier
	s_nop 0
	v_mov_b32_e32 v6, v227
	v_mov_b64_e32 v[2:3], s[48:49]
	v_ashrrev_i32_e32 v8, 3, v6
	v_lshlrev_b32_e32 v7, 4, v6
	v_mad_i64_i32 v[4:5], s[22:23], v8, s26, v[2:3]
	v_and_b32_e32 v0, 0x70, v7
	v_and_b32_e32 v144, 0xf0, v7
	v_add_u32_e32 v7, 0x200, v6
	v_lshl_add_u64 v[150:151], v[4:5], 0, v[0:1]
	v_lshl_add_u64 v[4:5], s[30:31], 0, v[144:145]
	v_ashrrev_i32_e32 v9, 4, v6
	v_ashrrev_i32_e32 v7, 4, v7
	v_and_b32_e32 v145, 31, v172
	v_ashrrev_i32_e32 v10, 5, v172
	v_mad_i64_i32 v[152:153], s[22:23], v9, s26, v[4:5]
	v_mad_i64_i32 v[154:155], s[22:23], v7, s26, v[4:5]
	v_or_b32_e32 v173, s1, v145
	v_lshlrev_b32_e32 v4, 3, v10
	v_mad_u64_u32 v[2:3], s[30:31], v173, s26, v[2:3]
	v_ashrrev_i32_e32 v5, 31, v4
	v_lshl_add_u64 v[156:157], v[4:5], 1, v[2:3]
	global_load_dwordx4 v[114:117], v[150:151], off offset:2048
	global_load_dwordx4 v[118:121], v[152:153], off
	global_load_dwordx4 v[122:125], v[154:155], off
	global_load_dwordx4 v[126:129], v[156:157], off
	global_load_dwordx4 v[130:133], v[156:157], off offset:32
	global_load_dwordx4 v[134:137], v[156:157], off offset:64
	global_load_dwordx4 v[138:141], v[156:157], off offset:96
	v_mul_lo_u32 v174, v8, s96
	v_add_u32_e32 v2, 0, v174
	v_add_u32_e32 v238, v2, v0
	v_add_u32_e32 v2, 0, v144
	v_mul_lo_u32 v175, v9, s77
	v_mul_lo_u32 v176, v7, s77
	v_lshlrev_b32_e32 v241, 2, v172
	v_add_u32_e32 v239, v2, v175
	v_add_u32_e32 v240, v2, v176
	v_and_b32_e32 v2, 16, v172
	v_lshrrev_b32_e32 v3, 2, v172
	v_lshlrev_b32_e32 v179, 2, v10
	v_and_or_b32 v3, v3, 3, v179
	v_and_or_b32 v2, v241, 12, v2
	v_lshlrev_b32_e32 v181, 1, v2
	v_mul_lo_u32 v182, v3, s77
	v_mov_b64_e32 v[2:3], s[28:29]
	v_and_b32_e32 v6, 15, v6
	v_mad_i64_i32 v[4:5], s[28:29], v7, s26, v[2:3]
	v_lshlrev_b32_e32 v6, 4, v6
	v_mov_b32_e32 v7, v1
	v_lshl_add_u64 v[4:5], v[4:5], 0, v[6:7]
	v_lshl_add_u64 v[146:147], s[16:17], 0, v[4:5]
	v_mad_i64_i32 v[4:5], s[28:29], v9, s26, v[2:3]
	v_lshl_add_u64 v[4:5], v[4:5], 0, v[6:7]
	v_mad_i64_i32 v[2:3], s[28:29], v8, s26, v[2:3]
	v_lshlrev_b32_e32 v178, 4, v10
	v_lshl_add_u64 v[148:149], s[16:17], 0, v[4:5]
	v_lshl_add_u64 v[158:159], v[2:3], 0, v[0:1]
	v_mov_b32_e32 v2, v1
	v_mov_b32_e32 v3, v1
	v_mov_b32_e32 v4, v1
	v_mov_b32_e32 v5, v1
	v_mov_b32_e32 v6, v1
	v_mov_b32_e32 v8, v1
	v_mov_b32_e32 v9, v1
	v_mov_b32_e32 v10, v1
	v_mov_b32_e32 v11, v1
	v_mov_b64_e32 v[64:65], v[16:17]
	v_mov_b64_e32 v[48:49], v[16:17]
	v_mov_b64_e32 v[32:33], v[16:17]
	v_mov_b64_e32 v[80:81], v[16:17]
	s_mov_b32 s22, 0
	v_mul_u32_u24_e32 v177, 0x90, v145
	v_cmp_gt_u32_e64 s[42:43], 32, v172
	v_lshl_add_u32 v180, v145, 2, s91
	v_subrev_u32_e32 v183, 32, v173
	v_subrev_u32_e32 v184, 33, v173
	v_subrev_u32_e32 v185, 34, v173
	v_subrev_u32_e32 v186, 35, v173
	v_add_u32_e32 v187, -8, v173
	v_subrev_u32_e32 v188, 40, v173
	v_add_u32_e32 v189, -9, v173
	v_subrev_u32_e32 v195, 41, v173
	v_add_u32_e32 v196, -10, v173
	v_subrev_u32_e32 v197, 42, v173
	v_add_u32_e32 v198, -11, v173
	v_subrev_u32_e32 v199, 43, v173
	v_add_u32_e32 v200, -16, v173
	v_subrev_u32_e32 v201, 48, v173
	v_subrev_u32_e32 v202, 17, v173
	v_subrev_u32_e32 v203, 49, v173
	v_subrev_u32_e32 v204, 18, v173
	v_subrev_u32_e32 v205, 50, v173
	v_subrev_u32_e32 v228, 19, v173
	v_subrev_u32_e32 v229, 51, v173
	v_subrev_u32_e32 v230, 24, v173
	v_subrev_u32_e32 v231, 56, v173
	v_subrev_u32_e32 v232, 25, v173
	v_subrev_u32_e32 v233, 57, v173
	v_subrev_u32_e32 v234, 26, v173
	v_subrev_u32_e32 v235, 58, v173
	v_subrev_u32_e32 v236, 27, v173
	v_subrev_u32_e32 v237, 59, v173
	v_lshl_add_u64 v[160:161], s[44:45], 0, v[158:159]
	v_mov_b64_e32 v[162:163], v[148:149]
	v_mov_b64_e32 v[164:165], v[146:147]
	v_mov_b64_e32 v[62:63], v[14:15]
	v_mov_b64_e32 v[60:61], v[12:13]
	v_mov_b64_e32 v[58:59], v[10:11]
	v_mov_b64_e32 v[56:57], v[8:9]
	v_mov_b64_e32 v[54:55], v[6:7]
	v_mov_b64_e32 v[52:53], v[4:5]
	v_mov_b64_e32 v[50:51], v[2:3]
	v_mov_b64_e32 v[46:47], v[14:15]
	v_mov_b64_e32 v[44:45], v[12:13]
	v_mov_b64_e32 v[42:43], v[10:11]
	v_mov_b64_e32 v[40:41], v[8:9]
	v_mov_b64_e32 v[38:39], v[6:7]
	v_mov_b64_e32 v[36:37], v[4:5]
	v_mov_b64_e32 v[34:35], v[2:3]
	v_mov_b64_e32 v[30:31], v[14:15]
	v_mov_b64_e32 v[28:29], v[12:13]
	v_mov_b64_e32 v[26:27], v[10:11]
	v_mov_b64_e32 v[24:25], v[8:9]
	v_mov_b64_e32 v[22:23], v[6:7]
	v_mov_b64_e32 v[20:21], v[4:5]
	v_mov_b64_e32 v[18:19], v[2:3]
	v_mov_b64_e32 v[78:79], v[14:15]
	v_mov_b64_e32 v[76:77], v[12:13]
	v_mov_b64_e32 v[74:75], v[10:11]
	v_mov_b64_e32 v[72:73], v[8:9]
	v_mov_b64_e32 v[70:71], v[6:7]
	v_mov_b64_e32 v[68:69], v[4:5]
	v_mov_b64_e32 v[66:67], v[2:3]
	s_waitcnt vmcnt(6)
	ds_write_b128 v238, v[114:117]
	s_waitcnt vmcnt(5)
	ds_write_b128 v239, v[118:121] offset:9216
	s_waitcnt vmcnt(4)
	ds_write_b128 v240, v[122:125] offset:9216
	s_waitcnt vmcnt(0) lgkmcnt(0)
	s_barrier
	s_cmp_lt_u32 s4, s5
	s_cselect_b64 s[28:29], -1, 0
	s_cmp_ge_u32 s4, s5
	s_cbranch_scc1 .LBB0_66

.LBB0_66:
	s_add_i32 s23, s4, -1
	s_and_b32 s23, s23, 1
	s_cmp_gt_u32 s22, s11
	s_cbranch_scc1 .LBB0_73
	s_mul_i32 s26, s23, 0x6900
	s_add_i32 s26, s26, 0
	v_add3_u32 v206, s26, v177, v178
	ds_read_b128 v[82:85], v206
	ds_read_b128 v[190:193], v206 offset:32
	ds_read_b128 v[98:101], v206 offset:4608
	s_add_i32 s30, s22, 63
	s_cmp_le_u32 s30, s1
	s_waitcnt lgkmcnt(2)
	v_mfma_f32_32x32x16_bf16 v[82:97], v[82:85], v[126:129], 0
	s_waitcnt lgkmcnt(1)
	v_mfma_f32_32x32x16_bf16 v[82:97], v[190:193], v[130:133], v[82:97]
	ds_read_b128 v[190:193], v206 offset:4640
	s_waitcnt lgkmcnt(1)
	v_mfma_f32_32x32x16_bf16 v[98:113], v[98:101], v[126:129], 0
	s_waitcnt lgkmcnt(0)
	v_mfma_f32_32x32x16_bf16 v[98:113], v[190:193], v[130:133], v[98:113]
	ds_read_b128 v[190:193], v206 offset:64
	s_waitcnt lgkmcnt(0)
	v_mfma_f32_32x32x16_bf16 v[82:97], v[190:193], v[134:137], v[82:97]
	ds_read_b128 v[190:193], v206 offset:4672
	s_waitcnt lgkmcnt(0)
	v_mfma_f32_32x32x16_bf16 v[98:113], v[190:193], v[134:137], v[98:113]
	ds_read_b128 v[190:193], v206 offset:96
	s_waitcnt lgkmcnt(0)
	v_mfma_f32_32x32x16_bf16 v[82:97], v[190:193], v[138:141], v[82:97]
	ds_read_b128 v[190:193], v206 offset:4704
	s_waitcnt lgkmcnt(0)
	v_mfma_f32_32x32x16_bf16 v[98:113], v[190:193], v[138:141], v[98:113]
	s_cbranch_scc1 .LBB0_69
	v_add_u32_e32 v190, s22, v179
	v_cmp_le_i32_e32 vcc, v190, v183
	v_add_u32_e32 v191, 2, v190
	s_nop 7
	v_cndmask_b32_e32 v98, v220, v98, vcc
	v_cmp_lt_i32_e32 vcc, v190, v173
	s_nop 1
	v_cndmask_b32_e32 v83, v220, v83, vcc
	v_cmp_le_i32_e32 vcc, v190, v173
	s_nop 1
	v_cndmask_b32_e32 v82, v220, v82, vcc
	v_cmp_le_i32_e32 vcc, v190, v184
	s_nop 1
	v_cndmask_b32_e32 v99, v220, v99, vcc
	v_cmp_le_i32_e32 vcc, v191, v173
	v_add_u32_e32 v191, 3, v190
	s_nop 0
	v_cndmask_b32_e32 v84, v220, v84, vcc
	v_cmp_le_i32_e32 vcc, v190, v185
	s_nop 1
	v_cndmask_b32_e32 v100, v220, v100, vcc
	v_cmp_le_i32_e32 vcc, v191, v173
	s_nop 1
	v_cndmask_b32_e32 v85, v220, v85, vcc
	v_cmp_le_i32_e32 vcc, v190, v186
	s_nop 1
	v_cndmask_b32_e32 v101, v220, v101, vcc
	v_cmp_le_i32_e32 vcc, v190, v187
	s_nop 1
	v_cndmask_b32_e32 v86, v220, v86, vcc
	v_cmp_le_i32_e32 vcc, v190, v188
	s_nop 1
	v_cndmask_b32_e32 v102, v220, v102, vcc
	v_cmp_le_i32_e32 vcc, v190, v189
	s_nop 1
	v_cndmask_b32_e32 v87, v220, v87, vcc
	v_cmp_le_i32_e32 vcc, v190, v195
	s_nop 1
	v_cndmask_b32_e32 v103, v220, v103, vcc
	v_cmp_le_i32_e32 vcc, v190, v196
	s_nop 1
	v_cndmask_b32_e32 v88, v220, v88, vcc
	v_cmp_le_i32_e32 vcc, v190, v197
	s_nop 1
	v_cndmask_b32_e32 v104, v220, v104, vcc
	v_cmp_le_i32_e32 vcc, v190, v198
	s_nop 1
	v_cndmask_b32_e32 v89, v220, v89, vcc
	v_cmp_le_i32_e32 vcc, v190, v199
	s_nop 1
	v_cndmask_b32_e32 v105, v220, v105, vcc
	v_cmp_le_i32_e32 vcc, v190, v200
	s_nop 1
	v_cndmask_b32_e32 v90, v220, v90, vcc
	v_cmp_le_i32_e32 vcc, v190, v201
	s_nop 1
	v_cndmask_b32_e32 v106, v220, v106, vcc
	v_cmp_le_i32_e32 vcc, v190, v202
	s_nop 1
	v_cndmask_b32_e32 v91, v220, v91, vcc
	v_cmp_le_i32_e32 vcc, v190, v203
	s_nop 1
	v_cndmask_b32_e32 v107, v220, v107, vcc
	v_cmp_le_i32_e32 vcc, v190, v204
	s_nop 1
	v_cndmask_b32_e32 v92, v220, v92, vcc
	v_cmp_le_i32_e32 vcc, v190, v205
	s_nop 1
	v_cndmask_b32_e32 v108, v220, v108, vcc
	v_cmp_le_i32_e32 vcc, v190, v228
	s_nop 1
	v_cndmask_b32_e32 v93, v220, v93, vcc
	v_cmp_le_i32_e32 vcc, v190, v229
	s_nop 1
	v_cndmask_b32_e32 v109, v220, v109, vcc
	v_cmp_le_i32_e32 vcc, v190, v230
	s_nop 1
	v_cndmask_b32_e32 v94, v220, v94, vcc
	v_cmp_le_i32_e32 vcc, v190, v231
	s_nop 1
	v_cndmask_b32_e32 v110, v220, v110, vcc
	v_cmp_le_i32_e32 vcc, v190, v232
	s_nop 1
	v_cndmask_b32_e32 v95, v220, v95, vcc
	v_cmp_le_i32_e32 vcc, v190, v233
	s_nop 1
	v_cndmask_b32_e32 v111, v220, v111, vcc
	v_cmp_le_i32_e32 vcc, v190, v234
	s_nop 1
	v_cndmask_b32_e32 v96, v220, v96, vcc
	v_cmp_le_i32_e32 vcc, v190, v235
	s_nop 1
	v_cndmask_b32_e32 v112, v220, v112, vcc
	v_cmp_le_i32_e32 vcc, v190, v236
	s_nop 1
	v_cndmask_b32_e32 v97, v220, v97, vcc
	v_cmp_le_i32_e32 vcc, v190, v237
	s_nop 1
	v_cndmask_b32_e32 v113, v220, v113, vcc

.LBB0_79:
	v_mov_b32_e32 v82, v2
	v_rcp_f32_e32 v2, v67
	v_mov_b32_e32 v83, v50
	v_mov_b32_e32 v85, v18
	v_mov_b32_e32 v50, v3
	v_mov_b32_e32 v18, v35
	v_pk_mul_f32 v[50:51], v[50:51], v[2:3] op_sel_hi:[1,0]
	v_pk_mul_f32 v[2:3], v[18:19], v[2:3] op_sel_hi:[1,0]
	v_mov_b32_e32 v18, v4
	v_rcp_f32_e32 v4, v69
	v_mov_b32_e32 v84, v34
	v_rcp_f32_e32 v34, v68
	v_mov_b32_e32 v19, v52
	v_mov_b32_e32 v69, v20
	v_mov_b32_e32 v52, v5
	v_mov_b32_e32 v20, v37
	v_pk_mul_f32 v[52:53], v[52:53], v[4:5] op_sel_hi:[1,0]
	v_pk_mul_f32 v[4:5], v[20:21], v[4:5] op_sel_hi:[1,0]
	v_mov_b32_e32 v20, v6
	v_rcp_f32_e32 v6, v71
	v_mov_b32_e32 v68, v36
	v_pk_mul_f32 v[18:19], v[18:19], v[34:35] op_sel_hi:[1,0]
	v_pk_mul_f32 v[34:35], v[68:69], v[34:35] op_sel_hi:[1,0]
	v_rcp_f32_e32 v36, v70
	v_mov_b32_e32 v21, v54
	v_mov_b32_e32 v69, v22
	v_mov_b32_e32 v54, v7
	v_mov_b32_e32 v22, v39
	v_pk_mul_f32 v[54:55], v[54:55], v[6:7] op_sel_hi:[1,0]
	v_pk_mul_f32 v[6:7], v[22:23], v[6:7] op_sel_hi:[1,0]
	v_mov_b32_e32 v22, v8
	v_rcp_f32_e32 v8, v73
	v_mov_b32_e32 v68, v38
	v_pk_mul_f32 v[20:21], v[20:21], v[36:37] op_sel_hi:[1,0]
	v_pk_mul_f32 v[36:37], v[68:69], v[36:37] op_sel_hi:[1,0]
	v_rcp_f32_e32 v38, v72
	v_mov_b32_e32 v23, v56
	v_mov_b32_e32 v69, v24
	v_mov_b32_e32 v56, v9
	v_mov_b32_e32 v24, v41
	v_pk_mul_f32 v[56:57], v[56:57], v[8:9] op_sel_hi:[1,0]
	v_pk_mul_f32 v[8:9], v[24:25], v[8:9] op_sel_hi:[1,0]
	v_mov_b32_e32 v24, v10
	v_rcp_f32_e32 v10, v75
	v_mov_b32_e32 v68, v40
	v_pk_mul_f32 v[22:23], v[22:23], v[38:39] op_sel_hi:[1,0]
	v_pk_mul_f32 v[38:39], v[68:69], v[38:39] op_sel_hi:[1,0]
	v_rcp_f32_e32 v40, v74
	v_mov_b32_e32 v25, v58
	v_mov_b32_e32 v69, v26
	v_mov_b32_e32 v58, v11
	v_mov_b32_e32 v26, v43
	v_pk_mul_f32 v[58:59], v[58:59], v[10:11] op_sel_hi:[1,0]
	v_pk_mul_f32 v[10:11], v[26:27], v[10:11] op_sel_hi:[1,0]
	v_mov_b32_e32 v26, v12
	v_rcp_f32_e32 v12, v77
	v_mov_b32_e32 v68, v42
	v_pk_mul_f32 v[24:25], v[24:25], v[40:41] op_sel_hi:[1,0]
	v_pk_mul_f32 v[40:41], v[68:69], v[40:41] op_sel_hi:[1,0]
	v_rcp_f32_e32 v42, v76
	v_mov_b32_e32 v27, v60
	v_mov_b32_e32 v69, v28
	v_mov_b32_e32 v60, v13
	v_mov_b32_e32 v28, v45
	v_pk_mul_f32 v[60:61], v[60:61], v[12:13] op_sel_hi:[1,0]
	v_pk_mul_f32 v[12:13], v[28:29], v[12:13] op_sel_hi:[1,0]
	v_mov_b32_e32 v28, v14
	v_rcp_f32_e32 v14, v79
	v_mov_b32_e32 v68, v44
	v_rcp_f32_e32 v66, v66
	v_pk_mul_f32 v[26:27], v[26:27], v[42:43] op_sel_hi:[1,0]
	v_pk_mul_f32 v[42:43], v[68:69], v[42:43] op_sel_hi:[1,0]
	v_rcp_f32_e32 v44, v78
	v_mov_b32_e32 v29, v62
	v_mov_b32_e32 v69, v30
	v_mov_b32_e32 v62, v15
	v_mov_b32_e32 v30, v47
	v_pk_mul_f32 v[62:63], v[62:63], v[14:15] op_sel_hi:[1,0]
	v_pk_mul_f32 v[14:15], v[30:31], v[14:15] op_sel_hi:[1,0]
	v_mov_b32_e32 v30, v16
	v_rcp_f32_e32 v16, v81
	v_readlane_b32 s4, v251, 9
	v_mov_b32_e32 v68, v46
	v_pk_mul_f32 v[82:83], v[82:83], v[66:67] op_sel_hi:[1,0]
	v_add_u32_e32 v160, s4, v241
	v_pk_mul_f32 v[66:67], v[84:85], v[66:67] op_sel_hi:[1,0]
	v_pk_mul_f32 v[28:29], v[28:29], v[44:45] op_sel_hi:[1,0]
	v_pk_mul_f32 v[44:45], v[68:69], v[44:45] op_sel_hi:[1,0]
	v_mov_b32_e32 v31, v64
	v_mov_b32_e32 v69, v32
	v_mov_b32_e32 v64, v17
	v_mov_b32_e32 v32, v49
	v_mov_b32_e32 v68, v48
	v_pk_mul_f32 v[64:65], v[64:65], v[16:17] op_sel_hi:[1,0]
	v_pk_mul_f32 v[16:17], v[32:33], v[16:17] op_sel_hi:[1,0]
	v_cvt_pk_bf16_f32 v33, v82, v83
	v_add_u32_e32 v32, 0, v160
	v_cvt_pk_bf16_f32 v48, v66, v67
	ds_write2st64_b32 v32, v33, v48 offset1:1
	v_cvt_pk_bf16_f32 v33, v50, v51
	v_cvt_pk_bf16_f32 v2, v2, v3
	ds_write2st64_b32 v32, v33, v2 offset0:2 offset1:3
	v_cvt_pk_bf16_f32 v2, v18, v19
	v_cvt_pk_bf16_f32 v3, v34, v35
	ds_write2st64_b32 v32, v2, v3 offset0:4 offset1:5
	v_cvt_pk_bf16_f32 v2, v52, v53
	v_cvt_pk_bf16_f32 v3, v4, v5
	ds_write2st64_b32 v32, v2, v3 offset0:6 offset1:7
	v_cvt_pk_bf16_f32 v2, v20, v21
	v_cvt_pk_bf16_f32 v3, v36, v37
	ds_write2st64_b32 v32, v2, v3 offset0:8 offset1:9
	v_cvt_pk_bf16_f32 v2, v54, v55
	v_cvt_pk_bf16_f32 v3, v6, v7
	ds_write2st64_b32 v32, v2, v3 offset0:10 offset1:11
	v_cvt_pk_bf16_f32 v2, v22, v23
	v_cvt_pk_bf16_f32 v3, v38, v39
	ds_write2st64_b32 v32, v2, v3 offset0:12 offset1:13
	v_cvt_pk_bf16_f32 v2, v56, v57
	v_cvt_pk_bf16_f32 v3, v8, v9
	ds_write2st64_b32 v32, v2, v3 offset0:14 offset1:15
	v_cvt_pk_bf16_f32 v2, v24, v25
	v_cvt_pk_bf16_f32 v3, v40, v41
	v_rcp_f32_e32 v46, v80
	ds_write2st64_b32 v32, v2, v3 offset0:16 offset1:17
	v_cvt_pk_bf16_f32 v2, v58, v59
	v_cvt_pk_bf16_f32 v3, v10, v11
	ds_write2st64_b32 v32, v2, v3 offset0:18 offset1:19
	v_cvt_pk_bf16_f32 v2, v26, v27
	v_cvt_pk_bf16_f32 v3, v42, v43
	ds_write2st64_b32 v32, v2, v3 offset0:20 offset1:21
	v_cvt_pk_bf16_f32 v2, v60, v61
	v_cvt_pk_bf16_f32 v3, v12, v13
	ds_write2st64_b32 v32, v2, v3 offset0:22 offset1:23
	v_cvt_pk_bf16_f32 v2, v28, v29
	v_cvt_pk_bf16_f32 v3, v44, v45
	v_pk_mul_f32 v[30:31], v[30:31], v[46:47] op_sel_hi:[1,0]
	v_pk_mul_f32 v[46:47], v[68:69], v[46:47] op_sel_hi:[1,0]
	ds_write2st64_b32 v32, v2, v3 offset0:24 offset1:25
	v_cvt_pk_bf16_f32 v2, v62, v63
	v_cvt_pk_bf16_f32 v3, v14, v15
	ds_write2st64_b32 v32, v2, v3 offset0:26 offset1:27
	v_cvt_pk_bf16_f32 v2, v30, v31
	v_cvt_pk_bf16_f32 v3, v46, v47
	ds_write2st64_b32 v32, v2, v3 offset0:28 offset1:29
	v_cvt_pk_bf16_f32 v2, v64, v65
	v_cvt_pk_bf16_f32 v3, v16, v17
	ds_write2st64_b32 v32, v2, v3 offset0:30 offset1:31
	global_load_dwordx4 v[114:117], v[150:151], off offset:2176
	global_load_dwordx4 v[130:133], v[152:153], off
	global_load_dwordx4 v[138:141], v[154:155], off
	global_load_dwordx4 v[118:121], v[156:157], off offset:128
	global_load_dwordx4 v[122:125], v[156:157], off offset:160
	global_load_dwordx4 v[126:129], v[156:157], off offset:192
	global_load_dwordx4 v[134:137], v[156:157], off offset:224
	v_mov_b32_e32 v16, v1
	v_mov_b32_e32 v17, v1
	v_mov_b32_e32 v2, v1
	v_mov_b32_e32 v3, v1
	v_mov_b32_e32 v4, v1
	v_mov_b32_e32 v5, v1
	v_mov_b32_e32 v6, v1
	v_mov_b32_e32 v7, v1
	v_mov_b32_e32 v8, v1
	v_mov_b32_e32 v9, v1
	v_mov_b32_e32 v10, v1
	v_mov_b32_e32 v11, v1
	v_mov_b32_e32 v12, v1
	v_mov_b32_e32 v13, v1
	v_mov_b32_e32 v14, v1
	v_mov_b32_e32 v15, v1
	v_mov_b64_e32 v[64:65], v[16:17]
	v_mov_b64_e32 v[32:33], v[16:17]
	v_mov_b64_e32 v[48:49], v[16:17]
	v_mov_b64_e32 v[80:81], v[16:17]
	v_lshl_add_u64 v[150:151], s[46:47], 0, v[158:159]
	v_mov_b32_e32 v153, 0xff800000
	s_mov_b32 s4, 0
	s_mov_b32 s22, 1
	v_mov_b64_e32 v[62:63], v[14:15]
	v_mov_b64_e32 v[60:61], v[12:13]
	v_mov_b64_e32 v[58:59], v[10:11]
	v_mov_b64_e32 v[56:57], v[8:9]
	v_mov_b64_e32 v[54:55], v[6:7]
	v_mov_b64_e32 v[52:53], v[4:5]
	v_mov_b64_e32 v[50:51], v[2:3]
	v_mov_b64_e32 v[30:31], v[14:15]
	v_mov_b64_e32 v[28:29], v[12:13]
	v_mov_b64_e32 v[26:27], v[10:11]
	v_mov_b64_e32 v[24:25], v[8:9]
	v_mov_b64_e32 v[22:23], v[6:7]
	v_mov_b64_e32 v[20:21], v[4:5]
	v_mov_b64_e32 v[18:19], v[2:3]
	v_mov_b64_e32 v[46:47], v[14:15]
	v_mov_b64_e32 v[44:45], v[12:13]
	v_mov_b64_e32 v[42:43], v[10:11]
	v_mov_b64_e32 v[40:41], v[8:9]
	v_mov_b64_e32 v[38:39], v[6:7]
	v_mov_b64_e32 v[36:37], v[4:5]
	v_mov_b64_e32 v[34:35], v[2:3]
	v_mov_b64_e32 v[78:79], v[14:15]
	v_mov_b64_e32 v[76:77], v[12:13]
	v_mov_b64_e32 v[74:75], v[10:11]
	v_mov_b64_e32 v[72:73], v[8:9]
	v_mov_b64_e32 v[70:71], v[6:7]
	v_mov_b64_e32 v[68:69], v[4:5]
	v_mov_b64_e32 v[66:67], v[2:3]
	s_waitcnt vmcnt(6)
	ds_write_b128 v238, v[114:117]
	s_waitcnt vmcnt(5)
	ds_write_b128 v239, v[130:133] offset:9216
	s_waitcnt vmcnt(4)
	ds_write_b128 v240, v[138:141] offset:9216
	s_waitcnt vmcnt(0) lgkmcnt(0)
	s_barrier
	s_cmp_lt_u32 s22, s5
	s_cselect_b64 s[28:29], -1, 0
	s_cmp_ge_u32 s22, s5
	s_cbranch_scc1 .LBB0_81

.LBB0_81:
	s_add_i32 s23, s22, -1
	s_and_b32 s23, s23, 1
	s_cmp_gt_u32 s4, s11
	s_cbranch_scc1 .LBB0_88
	s_mul_i32 s26, s23, 0x6900
	s_add_i32 s26, s26, 0
	v_add3_u32 v152, s26, v177, v178
	ds_read_b128 v[82:85], v152
	ds_read_b128 v[154:157], v152 offset:32
	ds_read_b128 v[98:101], v152 offset:4608
	s_add_i32 s30, s4, 63
	s_cmp_le_u32 s30, s1
	s_waitcnt lgkmcnt(2)
	v_mfma_f32_32x32x16_bf16 v[82:97], v[82:85], v[118:121], 0
	s_waitcnt lgkmcnt(1)
	v_mfma_f32_32x32x16_bf16 v[82:97], v[154:157], v[122:125], v[82:97]
	ds_read_b128 v[154:157], v152 offset:4640
	s_waitcnt lgkmcnt(1)
	v_mfma_f32_32x32x16_bf16 v[98:113], v[98:101], v[118:121], 0
	s_waitcnt lgkmcnt(0)
	v_mfma_f32_32x32x16_bf16 v[98:113], v[154:157], v[122:125], v[98:113]
	ds_read_b128 v[154:157], v152 offset:64
	s_waitcnt lgkmcnt(0)
	v_mfma_f32_32x32x16_bf16 v[82:97], v[154:157], v[126:129], v[82:97]
	ds_read_b128 v[154:157], v152 offset:4672
	s_waitcnt lgkmcnt(0)
	v_mfma_f32_32x32x16_bf16 v[98:113], v[154:157], v[126:129], v[98:113]
	ds_read_b128 v[154:157], v152 offset:96
	s_waitcnt lgkmcnt(0)
	v_mfma_f32_32x32x16_bf16 v[82:97], v[154:157], v[134:137], v[82:97]
	ds_read_b128 v[154:157], v152 offset:4704
	s_waitcnt lgkmcnt(0)
	v_mfma_f32_32x32x16_bf16 v[98:113], v[154:157], v[134:137], v[98:113]
	s_cbranch_scc1 .LBB0_84
	v_add_u32_e32 v152, s4, v179
	v_cmp_le_i32_e32 vcc, v152, v183
	v_add_u32_e32 v154, 2, v152
	s_nop 7
	v_cndmask_b32_e32 v98, v220, v98, vcc
	v_cmp_lt_i32_e32 vcc, v152, v173
	s_nop 1
	v_cndmask_b32_e32 v83, v220, v83, vcc
	v_cmp_le_i32_e32 vcc, v152, v173
	s_nop 1
	v_cndmask_b32_e32 v82, v220, v82, vcc
	v_cmp_le_i32_e32 vcc, v152, v184
	s_nop 1
	v_cndmask_b32_e32 v99, v220, v99, vcc
	v_cmp_le_i32_e32 vcc, v154, v173
	v_add_u32_e32 v154, 3, v152
	s_nop 0
	v_cndmask_b32_e32 v84, v220, v84, vcc
	v_cmp_le_i32_e32 vcc, v152, v185
	s_nop 1
	v_cndmask_b32_e32 v100, v220, v100, vcc
	v_cmp_le_i32_e32 vcc, v154, v173
	s_nop 1
	v_cndmask_b32_e32 v85, v220, v85, vcc
	v_cmp_le_i32_e32 vcc, v152, v186
	s_nop 1
	v_cndmask_b32_e32 v101, v220, v101, vcc
	v_cmp_le_i32_e32 vcc, v152, v187
	s_nop 1
	v_cndmask_b32_e32 v86, v220, v86, vcc
	v_cmp_le_i32_e32 vcc, v152, v188
	s_nop 1
	v_cndmask_b32_e32 v102, v220, v102, vcc
	v_cmp_le_i32_e32 vcc, v152, v189
	s_nop 1
	v_cndmask_b32_e32 v87, v220, v87, vcc
	v_cmp_le_i32_e32 vcc, v152, v195
	s_nop 1
	v_cndmask_b32_e32 v103, v220, v103, vcc
	v_cmp_le_i32_e32 vcc, v152, v196
	s_nop 1
	v_cndmask_b32_e32 v88, v220, v88, vcc
	v_cmp_le_i32_e32 vcc, v152, v197
	s_nop 1
	v_cndmask_b32_e32 v104, v220, v104, vcc
	v_cmp_le_i32_e32 vcc, v152, v198
	s_nop 1
	v_cndmask_b32_e32 v89, v220, v89, vcc
	v_cmp_le_i32_e32 vcc, v152, v199
	s_nop 1
	v_cndmask_b32_e32 v105, v220, v105, vcc
	v_cmp_le_i32_e32 vcc, v152, v200
	s_nop 1
	v_cndmask_b32_e32 v90, v220, v90, vcc
	v_cmp_le_i32_e32 vcc, v152, v201
	s_nop 1
	v_cndmask_b32_e32 v106, v220, v106, vcc
	v_cmp_le_i32_e32 vcc, v152, v202
	s_nop 1
	v_cndmask_b32_e32 v91, v220, v91, vcc
	v_cmp_le_i32_e32 vcc, v152, v203
	s_nop 1
	v_cndmask_b32_e32 v107, v220, v107, vcc
	v_cmp_le_i32_e32 vcc, v152, v204
	s_nop 1
	v_cndmask_b32_e32 v92, v220, v92, vcc
	v_cmp_le_i32_e32 vcc, v152, v205
	s_nop 1
	v_cndmask_b32_e32 v108, v220, v108, vcc
	v_cmp_le_i32_e32 vcc, v152, v228
	s_nop 1
	v_cndmask_b32_e32 v93, v220, v93, vcc
	v_cmp_le_i32_e32 vcc, v152, v229
	s_nop 1
	v_cndmask_b32_e32 v109, v220, v109, vcc
	v_cmp_le_i32_e32 vcc, v152, v230
	s_nop 1
	v_cndmask_b32_e32 v94, v220, v94, vcc
	v_cmp_le_i32_e32 vcc, v152, v231
	s_nop 1
	v_cndmask_b32_e32 v110, v220, v110, vcc
	v_cmp_le_i32_e32 vcc, v152, v232
	s_nop 1
	v_cndmask_b32_e32 v95, v220, v95, vcc
	v_cmp_le_i32_e32 vcc, v152, v233
	s_nop 1
	v_cndmask_b32_e32 v111, v220, v111, vcc
	v_cmp_le_i32_e32 vcc, v152, v234
	s_nop 1
	v_cndmask_b32_e32 v96, v220, v96, vcc
	v_cmp_le_i32_e32 vcc, v152, v235
	s_nop 1
	v_cndmask_b32_e32 v112, v220, v112, vcc
	v_cmp_le_i32_e32 vcc, v152, v236
	s_nop 1
	v_cndmask_b32_e32 v97, v220, v97, vcc
	v_cmp_le_i32_e32 vcc, v152, v237
	s_nop 1
	v_cndmask_b32_e32 v113, v220, v113, vcc
